# GEMM K-loops skip the two counted vmcnt waits of each unit's first K-iteration (nothing needed is outstanding; they only waited for the previous epilogue's stores); prologue drains to vmcnt(0)
# speedup vs baseline: 1.0016x; 1.0016x over previous
; #define PG8_STAGE(bufoff, gbase, voff) do { _Pragma("unroll") for (int _i = 0; _i < 2; ++_i) \
;         __builtin_amdgcn_global_load_lds((const unsigned*)((const char*)(gbase) + (voff)[_i]), (PG8_LAS unsigned*)(lds + (bufoff) + ldsw + _i * 8192), 16, 0, 0); } while (0)
; #define PG8_WAIT_V(n) asm volatile("s_waitcnt vmcnt(" #n ")" ::: "memory")
; #define PG8_BAR __builtin_amdgcn_s_barrier()
; template <class Epi, class Sched, bool ALIGN_EPI = false, bool SP2 = false>
; __device__ __forceinline__ void gemm_phase(PG8_LAS unsigned char* lds, const Sched& S, const Epi& E, int wave_id) {
;     ...
;     const int wid = __builtin_amdgcn_readfirstlane(tid >> 6), lane = tid & 63, wr = wid >> 2, wc = wid & 3, fr = lane & 15, fq = lane >> 4;
;     constexpr int K = 2048;
;     unsigned voffA[2], voffB[2];
; #pragma unroll
;     for (int i = 0; i < 2; ++i) { int R, C; stage_rc(tid * 16 + i * 8192, R, C); const int Rb = Epi::PERM ? ((R & ~31) + perm32(R & 31)) : R;
;         voffA[i] = (unsigned)(R * K + C) * 2u; voffB[i] = (unsigned)(Rb * K + C) * 2u; }
;     const size_t kstep = (size_t)(BK * 2);
;     const size_t hstep = (size_t)HALF * K * 2;
;     const unsigned ldsw = (unsigned)wid * 1024u;
;     const int aoff = lds_byte(wr * 64 + fr, fq * 8), boff = lds_byte(wc * 32 + fr, fq * 8);
;     ...
;         PG8_STAGE(PG8_SB(1, 0), cB + kstep, voffB); PG8_STAGE(PG8_SA(1, 0), cA + kstep, voffA); PG8_STAGE(PG8_SB(1, 1), cB + hstep + kstep, voffB);
;         PG8_WAIT_V(6); PG8_BAR;
.LBB0_83:
	v_readlane_b32 s19, v252, 3
	s_add_u32 s35, s12, 0x20800000
	s_mul_i32 s30, s19, 0x1500
	s_addc_u32 s46, s13, 0
	s_lshl_b64 s[20:21], s[30:31], 2
	s_add_u32 s20, s12, s20
	s_addc_u32 s21, s13, s21
	s_lshl_b32 s12, s18, 5
	s_and_b32 s47, s12, 0x60
	s_add_i32 m0, s23, 0x18000
	v_lshl_add_u64 v[8:9], v[8:9], 0, s[26:27]
	s_lshl_b32 s30, s17, 6
	s_lshl_b32 s17, s17, 13
	s_lshl_b32 s18, s47, 7
	s_waitcnt vmcnt(2)
	s_barrier
	global_load_lds_dwordx4 v[8:9], off
	v_lshl_add_u64 v[6:7], v[6:7], 0, s[26:27]
	s_add_i32 m0, s23, 0x1a000
	s_add_i32 s48, s23, 0x8000
	s_add_i32 s49, s23, 0xa000
	global_load_lds_dwordx4 v[6:7], off
	v_lshl_add_u64 v[2:3], v[2:3], 0, s[26:27]
	s_mov_b32 m0, s48
	s_add_u32 s12, s42, 0x80080
	global_load_lds_dwordx4 v[2:3], off
	v_lshl_add_u64 v[2:3], v[4:5], 0, s[26:27]
	s_mov_b32 m0, s49
	s_addc_u32 s13, s43, 0
	global_load_lds_dwordx4 v[2:3], off
	s_add_i32 m0, s23, 0x1c000
	v_lshl_add_u64 v[2:3], s[12:13], 0, v[0:1]
	global_load_lds_dwordx4 v[2:3], off
	v_lshl_add_u64 v[2:3], s[12:13], 0, v[150:151]
	s_add_i32 m0, s23, 0x1e000
	v_lshlrev_b32_e32 v6, 2, v10
	global_load_lds_dwordx4 v[2:3], off
	v_bfe_u32 v3, v10, 4, 2
	v_and_b32_e32 v2, 15, v10
	v_lshlrev_b32_e32 v4, 4, v3
	v_lshl_or_b32 v5, v2, 6, v4
	v_and_b32_e32 v6, 32, v6
	v_bitop3_b32 v7, v5, s17, v6 bitop3:0xde
	v_bitop3_b32 v164, v5, s18, v6 bitop3:0xde
	v_mul_u32_u24_e32 v5, 0x2a00, v2
	v_lshlrev_b32_e32 v2, 5, v3
	v_mov_b32_e32 v3, v1
	s_cmpk_lt_u32 s16, 0x100
	v_lshl_add_u64 v[2:3], s[20:21], 0, v[2:3]
	s_mov_b64 s[16:17], 0x100000
	v_lshl_add_u64 v[152:153], v[2:3], 0, s[16:17]
	v_lshlrev_b32_e32 v2, 15, v11
	v_and_b32_e32 v2, 0xffff0000, v2
	v_lshl_add_u32 v2, v12, 12, v2
	v_and_b32_e32 v3, 1, v11
	v_lshl_or_b32 v2, v3, 6, v2
	v_lshl_add_u32 v156, v13, 1, v2
	v_lshlrev_b32_e32 v2, 15, v14
	v_and_b32_e32 v2, 0xffff0000, v2
	s_waitcnt vmcnt(0)
	v_lshl_add_u32 v2, v15, 12, v2
	v_and_b32_e32 v3, 1, v14
	v_lshl_or_b32 v2, v3, 6, v2
	s_cselect_b64 s[12:13], -1, 0
	v_or_b32_e32 v154, v4, v5
	v_mov_b32_e32 v155, v1
	s_or_b32 s50, s30, 16
	s_or_b32 s51, s30, 32
	s_or_b32 s52, s30, 48
	v_mov_b32_e32 v157, v1
	v_lshl_add_u32 v158, v16, 1, v2
	v_mov_b32_e32 v159, v1
	s_mov_b32 s53, 0
	v_add_u32_e32 v165, 0, v7
	s_mov_b64 s[40:41], s[42:43]
	s_mov_b64 s[28:29], s[44:45]
	s_barrier
	s_branch .LBB0_86

; #define PG8_STAGE(bufoff, gbase, voff) do { _Pragma("unroll") for (int _i = 0; _i < 2; ++_i) \
;         __builtin_amdgcn_global_load_lds((const unsigned*)((const char*)(gbase) + (voff)[_i]), (PG8_LAS unsigned*)(lds + (bufoff) + ldsw + _i * 8192), 16, 0, 0); } while (0)
; #define PG8_LDA(dst, b, h) do { _Pragma("unroll") for (int m = 0; m < 4; ++m) _Pragma("unroll") for (int k = 0; k < 2; ++k) dst[m][k] = *(const PG8_LAS bf16x8*)(lds + PG8_SA(b, h) + aoff + m * 2048 + k * 1024); } while (0)
; #define PG8_LDB(dst, b, h) do { _Pragma("unroll") for (int n = 0; n < 2; ++n) _Pragma("unroll") for (int k = 0; k < 2; ++k) dst[n][k] = *(const PG8_LAS bf16x8*)(lds + PG8_SB(b, h) + boff + n * 2048 + k * 1024); } while (0)
; #define PG8_MMA(ai, bj, At, Bt) do { __builtin_amdgcn_s_setprio(1); _Pragma("unroll") for (int m = 0; m < 4; ++m) _Pragma("unroll") for (int n = 0; n < 2; ++n) _Pragma("unroll") for (int k = 0; k < 2; ++k) \
;         acc[ai][bj][m][n] = __builtin_amdgcn_mfma_f32_16x16x32_bf16(Bt[n][k], At[m][k], acc[ai][bj][m][n], 0, 0, 0); __builtin_amdgcn_s_setprio(0); } while (0)
; #define PG8_WAIT_V(n) asm volatile("s_waitcnt vmcnt(" #n ")" ::: "memory")
; #define PG8_BAR __builtin_amdgcn_s_barrier()
; template <class Epi, class Sched, bool ALIGN_EPI = false, bool SP2 = false>
; __device__ __forceinline__ void gemm_phase(PG8_LAS unsigned char* lds, const Sched& S, const Epi& E, int wave_id) {
;     ...
;         for (int t = 0; t < nt; t += 2) {
;             const bool last = (t == nt - 2);
;             const char* a1 = cA + (size_t)(t + 1) * kstep;
;             const char* a2 = last ? nA : cA + (size_t)(t + 2) * kstep; const char* b2 = last ? nB : cB + (size_t)(t + 2) * kstep;
;             const char* a3 = a2 + kstep; const char* b3 = b2 + kstep;
;             if (last && has_next) S.a_ready(nxt);
;             if constexpr (SP2) {
;             PG8_LDB(B0, 0, 0); PG8_LDB(B1, 0, 1); PG8_SCHED; PG8_LDA(At, 0, 0); PG8_STAGE(PG8_SA(1, 1), a1 + hstep, voffA);
;             PG8_WAIT_V(8); PG8_WAIT_L(0); PG8_BAR; PG8_MMA(0, 0, At, B0); PG8_MMA(0, 1, At, B1); PG8_BAR; PG8_SCHED;
;             PG8_LDA(At, 0, 1); PG8_STAGE(PG8_SB(0, 0), b2, voffB); PG8_STAGE(PG8_SB(0, 1), b2 + hstep, voffB); PG8_STAGE(PG8_SA(0, 0), a2, voffA);
;             PG8_WAIT_V(8); PG8_WAIT_L(0); PG8_BAR; PG8_MMA(1, 0, At, B0); PG8_MMA(1, 1, At, B1); PG8_BAR; PG8_SCHED;
.LBB0_89:
	s_add_u32 s20, s38, 0xfff80080
	s_addc_u32 s21, s39, -1
	s_add_i32 s60, 0, 0x10000
	s_cmp_eq_u32 s19, 28
	s_cselect_b32 s45, s29, s21
	s_cselect_b32 s44, s28, s20
	s_cselect_b32 s43, s41, s17
	s_cselect_b32 s42, s40, s16
	s_add_i32 s66, 0, 0x14000
	v_add_u32_e32 v54, s60, v164
	v_add_u32_e32 v174, s66, v164
	ds_read_b128 v[34:37], v54
	ds_read_b128 v[38:41], v54 offset:1024
	ds_read_b128 v[50:53], v54 offset:2048
	ds_read_b128 v[54:57], v54 offset:3072
	ds_read_b128 v[160:163], v174
	ds_read_b128 v[166:169], v174 offset:1024
	ds_read_b128 v[170:173], v174 offset:2048
	ds_read_b128 v[174:177], v174 offset:3072
	s_add_i32 m0, s23, 0xc000
	ds_read_b128 v[178:181], v165
	ds_read_b128 v[182:185], v165 offset:1024
	ds_read_b128 v[186:189], v165 offset:2048
	ds_read_b128 v[190:193], v165 offset:3072
	ds_read_b128 v[196:199], v165 offset:4096
	ds_read_b128 v[200:203], v165 offset:5120
	ds_read_b128 v[204:207], v165 offset:6144
	ds_read_b128 v[208:211], v165 offset:7168
	global_load_lds_dwordx4 v156, s[38:39]
	s_add_i32 m0, s23, 0xe000
	s_nop 0
	global_load_lds_dwordx4 v158, s[38:39]
	s_cmp_eq_u32 s19, -2
	s_cbranch_scc1 .Lfiw_0_0
	s_waitcnt vmcnt(8)
.Lfiw_0_0:
	s_waitcnt lgkmcnt(0)
	s_barrier
	s_setprio 1
	s_waitcnt lgkmcnt(0)
	v_mfma_f32_16x16x32_bf16 v[142:145], v[34:37], v[178:181], v[142:145]
	v_mfma_f32_16x16x32_bf16 v[138:141], v[50:53], v[178:181], v[138:141]
	v_mfma_f32_16x16x32_bf16 v[126:129], v[34:37], v[186:189], v[126:129]
	v_mfma_f32_16x16x32_bf16 v[122:125], v[50:53], v[186:189], v[122:125]
	v_mfma_f32_16x16x32_bf16 v[110:113], v[34:37], v[196:199], v[110:113]
	v_mfma_f32_16x16x32_bf16 v[106:109], v[50:53], v[196:199], v[106:109]
	v_mfma_f32_16x16x32_bf16 v[94:97], v[34:37], v[204:207], v[94:97]
	v_mfma_f32_16x16x32_bf16 v[90:93], v[50:53], v[204:207], v[90:93]
	v_mfma_f32_16x16x32_bf16 v[142:145], v[38:41], v[182:185], v[142:145]
	v_mfma_f32_16x16x32_bf16 v[138:141], v[54:57], v[182:185], v[138:141]
	v_mfma_f32_16x16x32_bf16 v[126:129], v[38:41], v[190:193], v[126:129]
	v_mfma_f32_16x16x32_bf16 v[122:125], v[54:57], v[190:193], v[122:125]
	v_mfma_f32_16x16x32_bf16 v[110:113], v[38:41], v[200:203], v[110:113]
	v_mfma_f32_16x16x32_bf16 v[106:109], v[54:57], v[200:203], v[106:109]
	v_mfma_f32_16x16x32_bf16 v[94:97], v[38:41], v[208:211], v[94:97]
	v_mfma_f32_16x16x32_bf16 v[90:93], v[54:57], v[208:211], v[90:93]
	s_setprio 0
	s_setprio 1
	v_mfma_f32_16x16x32_bf16 v[134:137], v[160:163], v[178:181], v[134:137]
	v_mfma_f32_16x16x32_bf16 v[130:133], v[170:173], v[178:181], v[130:133]
	v_mfma_f32_16x16x32_bf16 v[118:121], v[160:163], v[186:189], v[118:121]
	v_mfma_f32_16x16x32_bf16 v[114:117], v[170:173], v[186:189], v[114:117]
	v_mfma_f32_16x16x32_bf16 v[102:105], v[160:163], v[196:199], v[102:105]
	v_mfma_f32_16x16x32_bf16 v[98:101], v[170:173], v[196:199], v[98:101]
	v_mfma_f32_16x16x32_bf16 v[86:89], v[160:163], v[204:207], v[86:89]
	v_mfma_f32_16x16x32_bf16 v[82:85], v[170:173], v[204:207], v[82:85]
	v_mfma_f32_16x16x32_bf16 v[134:137], v[166:169], v[182:185], v[134:137]
	v_mfma_f32_16x16x32_bf16 v[130:133], v[174:177], v[182:185], v[130:133]
	v_mfma_f32_16x16x32_bf16 v[118:121], v[166:169], v[190:193], v[118:121]
	v_mfma_f32_16x16x32_bf16 v[114:117], v[174:177], v[190:193], v[114:117]
	v_mfma_f32_16x16x32_bf16 v[102:105], v[166:169], v[200:203], v[102:105]
	v_mfma_f32_16x16x32_bf16 v[98:101], v[174:177], v[200:203], v[98:101]
	v_mfma_f32_16x16x32_bf16 v[86:89], v[166:169], v[208:211], v[86:89]
	v_mfma_f32_16x16x32_bf16 v[82:85], v[174:177], v[208:211], v[82:85]
	s_setprio 0
	s_barrier
	s_add_i32 s20, s60, s22
	s_mov_b32 m0, s20
	ds_read_b128 v[178:181], v165 offset:16384
	ds_read_b128 v[182:185], v165 offset:17408
	ds_read_b128 v[186:189], v165 offset:18432
	ds_read_b128 v[190:193], v165 offset:19456
	ds_read_b128 v[196:199], v165 offset:20480
	ds_read_b128 v[200:203], v165 offset:21504
	ds_read_b128 v[204:207], v165 offset:22528
	ds_read_b128 v[208:211], v165 offset:23552
	global_load_lds_dwordx4 v0, s[42:43]
	s_add_i32 m0, s20, 0x2000
	s_add_u32 s20, s42, 0x80000
	s_addc_u32 s21, s43, 0
	s_add_i32 s60, s66, s22
	global_load_lds_dwordx4 v150, s[42:43]
	s_mov_b32 m0, s60
	s_nop 0
	global_load_lds_dwordx4 v0, s[20:21]
	s_add_i32 m0, s60, 0x2000
	s_nop 0
	global_load_lds_dwordx4 v150, s[20:21]
	s_mov_b32 m0, s23
	s_nop 0
	global_load_lds_dwordx4 v146, s[44:45]
	s_mov_b32 m0, s24
	s_nop 0
	global_load_lds_dwordx4 v148, s[44:45]
	s_cmp_eq_u32 s19, -2
	s_cbranch_scc1 .Lfiw_0_1
	s_waitcnt vmcnt(8)
; #define PG8_STAGE(bufoff, gbase, voff) do { _Pragma("unroll") for (int _i = 0; _i < 2; ++_i) \
;         __builtin_amdgcn_global_load_lds((const unsigned*)((const char*)(gbase) + (voff)[_i]), (PG8_LAS unsigned*)(lds + (bufoff) + ldsw + _i * 8192), 16, 0, 0); } while (0)
; #define PG8_LDA(dst, b, h) do { _Pragma("unroll") for (int m = 0; m < 4; ++m) _Pragma("unroll") for (int k = 0; k < 2; ++k) dst[m][k] = *(const PG8_LAS bf16x8*)(lds + PG8_SA(b, h) + aoff + m * 2048 + k * 1024); } while (0)
; #define PG8_LDB(dst, b, h) do { _Pragma("unroll") for (int n = 0; n < 2; ++n) _Pragma("unroll") for (int k = 0; k < 2; ++k) dst[n][k] = *(const PG8_LAS bf16x8*)(lds + PG8_SB(b, h) + boff + n * 2048 + k * 1024); } while (0)
; #define PG8_MMA(ai, bj, At, Bt) do { __builtin_amdgcn_s_setprio(1); _Pragma("unroll") for (int m = 0; m < 4; ++m) _Pragma("unroll") for (int n = 0; n < 2; ++n) _Pragma("unroll") for (int k = 0; k < 2; ++k) \
;         acc[ai][bj][m][n] = __builtin_amdgcn_mfma_f32_16x16x32_bf16(Bt[n][k], At[m][k], acc[ai][bj][m][n], 0, 0, 0); __builtin_amdgcn_s_setprio(0); } while (0)
; #define PG8_WAIT_V(n) asm volatile("s_waitcnt vmcnt(" #n ")" ::: "memory")
; #define PG8_WAIT_L(n) asm volatile("s_waitcnt lgkmcnt(" #n ")" ::: "memory")
; #define PG8_BAR __builtin_amdgcn_s_barrier()
; #define PG8_SCHED __builtin_amdgcn_sched_barrier(0)
; template <class Epi, class Sched, bool ALIGN_EPI = false, bool SP2 = false>
; __device__ __forceinline__ void gemm_phase(PG8_LAS unsigned char* lds, const Sched& S, const Epi& E, int wave_id) {
;     ...
;             PG8_WAIT_V(8); PG8_WAIT_L(0); PG8_BAR; PG8_MMA(1, 0, At, B0); PG8_MMA(1, 1, At, B1); PG8_BAR; PG8_SCHED;
;             PG8_LDB(B0, 1, 0); PG8_LDB(B1, 1, 1); PG8_SCHED; PG8_LDA(At, 1, 0); PG8_STAGE(PG8_SA(0, 1), a2 + hstep, voffA);
;             PG8_WAIT_V(8); PG8_WAIT_L(0); PG8_BAR; PG8_MMA(0, 0, At, B0); PG8_MMA(0, 1, At, B1); PG8_BAR; PG8_SCHED;
.Lfiw_0_1:
	s_waitcnt lgkmcnt(0)
	s_barrier
	s_setprio 1
	s_waitcnt lgkmcnt(0)
	v_mfma_f32_16x16x32_bf16 v[78:81], v[34:37], v[178:181], v[78:81]
	v_mfma_f32_16x16x32_bf16 v[74:77], v[50:53], v[178:181], v[74:77]
	v_mfma_f32_16x16x32_bf16 v[62:65], v[34:37], v[186:189], v[62:65]
	v_mfma_f32_16x16x32_bf16 v[58:61], v[50:53], v[186:189], v[58:61]
	v_mfma_f32_16x16x32_bf16 v[30:33], v[34:37], v[196:199], v[30:33]
	v_mfma_f32_16x16x32_bf16 v[26:29], v[50:53], v[196:199], v[26:29]
	v_mfma_f32_16x16x32_bf16 v[14:17], v[34:37], v[204:207], v[14:17]
	v_mfma_f32_16x16x32_bf16 v[10:13], v[50:53], v[204:207], v[10:13]
	v_mfma_f32_16x16x32_bf16 v[78:81], v[38:41], v[182:185], v[78:81]
	v_mfma_f32_16x16x32_bf16 v[74:77], v[54:57], v[182:185], v[74:77]
	v_mfma_f32_16x16x32_bf16 v[62:65], v[38:41], v[190:193], v[62:65]
	v_mfma_f32_16x16x32_bf16 v[58:61], v[54:57], v[190:193], v[58:61]
	v_mfma_f32_16x16x32_bf16 v[30:33], v[38:41], v[200:203], v[30:33]
	v_mfma_f32_16x16x32_bf16 v[26:29], v[54:57], v[200:203], v[26:29]
	v_mfma_f32_16x16x32_bf16 v[14:17], v[38:41], v[208:211], v[14:17]
	v_mfma_f32_16x16x32_bf16 v[10:13], v[54:57], v[208:211], v[10:13]
	s_setprio 0
	s_setprio 1
	v_mfma_f32_16x16x32_bf16 v[46:49], v[160:163], v[186:189], v[46:49]
	v_mfma_f32_16x16x32_bf16 v[42:45], v[170:173], v[186:189], v[42:45]
	v_mfma_f32_16x16x32_bf16 v[22:25], v[160:163], v[196:199], v[22:25]
	v_mfma_f32_16x16x32_bf16 v[18:21], v[170:173], v[196:199], v[18:21]
	v_mfma_f32_16x16x32_bf16 v[6:9], v[160:163], v[204:207], v[6:9]
	v_mfma_f32_16x16x32_bf16 v[2:5], v[170:173], v[204:207], v[2:5]
	v_mfma_f32_16x16x32_bf16 v[34:37], v[160:163], v[178:181], v[70:73]
	v_mfma_f32_16x16x32_bf16 v[38:41], v[170:173], v[178:181], v[66:69]
	v_mfma_f32_16x16x32_bf16 v[46:49], v[166:169], v[190:193], v[46:49]
	v_mfma_f32_16x16x32_bf16 v[42:45], v[174:177], v[190:193], v[42:45]
	v_mfma_f32_16x16x32_bf16 v[22:25], v[166:169], v[200:203], v[22:25]
	v_mfma_f32_16x16x32_bf16 v[18:21], v[174:177], v[200:203], v[18:21]
	v_mfma_f32_16x16x32_bf16 v[6:9], v[166:169], v[208:211], v[6:9]
	v_mfma_f32_16x16x32_bf16 v[2:5], v[174:177], v[208:211], v[2:5]
	v_mfma_f32_16x16x32_bf16 v[34:37], v[166:169], v[182:185], v[34:37]
	v_mfma_f32_16x16x32_bf16 v[38:41], v[174:177], v[182:185], v[38:41]
	s_setprio 0
	s_barrier
	s_add_i32 s60, 0, 0x18000
	s_add_i32 s66, 0, 0x1c000
	v_add_u32_e32 v70, s60, v164
	v_add_u32_e32 v174, s66, v164
	ds_read_b128 v[50:53], v70
	ds_read_b128 v[54:57], v70 offset:1024
	ds_read_b128 v[66:69], v70 offset:2048
	ds_read_b128 v[70:73], v70 offset:3072
	ds_read_b128 v[160:163], v174
	ds_read_b128 v[166:169], v174 offset:1024
	ds_read_b128 v[170:173], v174 offset:2048
	ds_read_b128 v[174:177], v174 offset:3072
	s_add_u32 s20, s44, 0x80000
	s_addc_u32 s21, s45, 0
	s_mov_b32 m0, s25
	ds_read_b128 v[178:181], v165 offset:32768
	ds_read_b128 v[182:185], v165 offset:33792
	ds_read_b128 v[186:189], v165 offset:34816
	ds_read_b128 v[190:193], v165 offset:35840
	ds_read_b128 v[196:199], v165 offset:36864
	ds_read_b128 v[200:203], v165 offset:37888
	ds_read_b128 v[204:207], v165 offset:38912
	ds_read_b128 v[208:211], v165 offset:39936
	global_load_lds_dwordx4 v146, s[20:21]
	s_mov_b32 m0, s33
	s_nop 0
	global_load_lds_dwordx4 v148, s[20:21]
	s_waitcnt vmcnt(8)
	s_waitcnt lgkmcnt(0)
	s_barrier
	s_setprio 1
	s_waitcnt lgkmcnt(0)
	v_mfma_f32_16x16x32_bf16 v[142:145], v[50:53], v[178:181], v[142:145]
	v_mfma_f32_16x16x32_bf16 v[138:141], v[66:69], v[178:181], v[138:141]
	v_mfma_f32_16x16x32_bf16 v[126:129], v[50:53], v[186:189], v[126:129]
	v_mfma_f32_16x16x32_bf16 v[122:125], v[66:69], v[186:189], v[122:125]
	v_mfma_f32_16x16x32_bf16 v[110:113], v[50:53], v[196:199], v[110:113]
	v_mfma_f32_16x16x32_bf16 v[106:109], v[66:69], v[196:199], v[106:109]
	v_mfma_f32_16x16x32_bf16 v[94:97], v[50:53], v[204:207], v[94:97]
	v_mfma_f32_16x16x32_bf16 v[90:93], v[66:69], v[204:207], v[90:93]
	v_mfma_f32_16x16x32_bf16 v[142:145], v[54:57], v[182:185], v[142:145]
	v_mfma_f32_16x16x32_bf16 v[138:141], v[70:73], v[182:185], v[138:141]
	v_mfma_f32_16x16x32_bf16 v[126:129], v[54:57], v[190:193], v[126:129]
	v_mfma_f32_16x16x32_bf16 v[122:125], v[70:73], v[190:193], v[122:125]
	v_mfma_f32_16x16x32_bf16 v[110:113], v[54:57], v[200:203], v[110:113]
	v_mfma_f32_16x16x32_bf16 v[106:109], v[70:73], v[200:203], v[106:109]
	v_mfma_f32_16x16x32_bf16 v[94:97], v[54:57], v[208:211], v[94:97]
	v_mfma_f32_16x16x32_bf16 v[90:93], v[70:73], v[208:211], v[90:93]
	s_setprio 0
	s_setprio 1
	v_mfma_f32_16x16x32_bf16 v[134:137], v[160:163], v[178:181], v[134:137]
	v_mfma_f32_16x16x32_bf16 v[130:133], v[170:173], v[178:181], v[130:133]
	v_mfma_f32_16x16x32_bf16 v[118:121], v[160:163], v[186:189], v[118:121]
	v_mfma_f32_16x16x32_bf16 v[114:117], v[170:173], v[186:189], v[114:117]
	v_mfma_f32_16x16x32_bf16 v[102:105], v[160:163], v[196:199], v[102:105]
	v_mfma_f32_16x16x32_bf16 v[98:101], v[170:173], v[196:199], v[98:101]
	v_mfma_f32_16x16x32_bf16 v[86:89], v[160:163], v[204:207], v[86:89]
	v_mfma_f32_16x16x32_bf16 v[82:85], v[170:173], v[204:207], v[82:85]
	v_mfma_f32_16x16x32_bf16 v[134:137], v[166:169], v[182:185], v[134:137]
	v_mfma_f32_16x16x32_bf16 v[130:133], v[174:177], v[182:185], v[130:133]
	v_mfma_f32_16x16x32_bf16 v[118:121], v[166:169], v[190:193], v[118:121]
	v_mfma_f32_16x16x32_bf16 v[114:117], v[174:177], v[190:193], v[114:117]
	v_mfma_f32_16x16x32_bf16 v[102:105], v[166:169], v[200:203], v[102:105]
	v_mfma_f32_16x16x32_bf16 v[98:101], v[174:177], v[200:203], v[98:101]
	v_mfma_f32_16x16x32_bf16 v[86:89], v[166:169], v[208:211], v[86:89]
	v_mfma_f32_16x16x32_bf16 v[82:85], v[174:177], v[208:211], v[82:85]
	s_setprio 0
	s_barrier
; #define PG8_STAGE(bufoff, gbase, voff) do { _Pragma("unroll") for (int _i = 0; _i < 2; ++_i) \
;         __builtin_amdgcn_global_load_lds((const unsigned*)((const char*)(gbase) + (voff)[_i]), (PG8_LAS unsigned*)(lds + (bufoff) + ldsw + _i * 8192), 16, 0, 0); } while (0)
; #define PG8_LDA(dst, b, h) do { _Pragma("unroll") for (int m = 0; m < 4; ++m) _Pragma("unroll") for (int k = 0; k < 2; ++k) dst[m][k] = *(const PG8_LAS bf16x8*)(lds + PG8_SA(b, h) + aoff + m * 2048 + k * 1024); } while (0)
; #define PG8_MMA(ai, bj, At, Bt) do { __builtin_amdgcn_s_setprio(1); _Pragma("unroll") for (int m = 0; m < 4; ++m) _Pragma("unroll") for (int n = 0; n < 2; ++n) _Pragma("unroll") for (int k = 0; k < 2; ++k) \
;         acc[ai][bj][m][n] = __builtin_amdgcn_mfma_f32_16x16x32_bf16(Bt[n][k], At[m][k], acc[ai][bj][m][n], 0, 0, 0); __builtin_amdgcn_s_setprio(0); } while (0)
; #define PG8_WAIT_V(n) asm volatile("s_waitcnt vmcnt(" #n ")" ::: "memory")
; #define PG8_WAIT_L(n) asm volatile("s_waitcnt lgkmcnt(" #n ")" ::: "memory")
; #define PG8_BAR __builtin_amdgcn_s_barrier()
; #define PG8_SCHED __builtin_amdgcn_sched_barrier(0)
; template <class Epi, class Sched, bool ALIGN_EPI = false, bool SP2 = false>
; __device__ __forceinline__ void gemm_phase(PG8_LAS unsigned char* lds, const Sched& S, const Epi& E, int wave_id) {
;     ...
;             PG8_LDA(At, 1, 1); PG8_STAGE(PG8_SB(1, 0), b3, voffB); PG8_STAGE(PG8_SB(1, 1), b3 + hstep, voffB); PG8_STAGE(PG8_SA(1, 0), a3, voffA);
;             PG8_WAIT_V(8); PG8_WAIT_L(0); PG8_BAR; PG8_MMA(1, 0, At, B0); PG8_MMA(1, 1, At, B1); PG8_BAR; PG8_SCHED;
	s_add_i32 s20, s60, s22
	s_sub_i32 m0, s20, 0x80
	ds_read_b128 v[178:181], v165 offset:49152
	ds_read_b128 v[182:185], v165 offset:50176
	ds_read_b128 v[186:189], v165 offset:51200
	ds_read_b128 v[190:193], v165 offset:52224
	ds_read_b128 v[196:199], v165 offset:53248
	ds_read_b128 v[200:203], v165 offset:54272
	ds_read_b128 v[204:207], v165 offset:55296
	ds_read_b128 v[208:211], v165 offset:56320
	global_load_lds_dwordx4 v0, s[42:43] offset:128
	s_add_i32 m0, s20, 0x1f80
	s_add_u32 s20, s42, 0x80080
	s_addc_u32 s21, s43, 0
	s_add_i32 s98, s66, s22
	global_load_lds_dwordx4 v150, s[42:43] offset:128
	s_mov_b32 m0, s98
	s_nop 0
	global_load_lds_dwordx4 v0, s[20:21]
	s_add_i32 m0, s98, 0x2000
	s_nop 0
	global_load_lds_dwordx4 v150, s[20:21]
	s_sub_i32 m0, s48, 0x80
	s_nop 0
	global_load_lds_dwordx4 v146, s[44:45] offset:128
	s_sub_i32 m0, s49, 0x80
	s_nop 0
	global_load_lds_dwordx4 v148, s[44:45] offset:128
	s_waitcnt vmcnt(8)
	s_waitcnt lgkmcnt(0)
	s_barrier
	s_setprio 1
	s_waitcnt lgkmcnt(0)
	v_mfma_f32_16x16x32_bf16 v[78:81], v[50:53], v[178:181], v[78:81]
	v_mfma_f32_16x16x32_bf16 v[74:77], v[66:69], v[178:181], v[74:77]
	v_mfma_f32_16x16x32_bf16 v[62:65], v[50:53], v[186:189], v[62:65]
	v_mfma_f32_16x16x32_bf16 v[58:61], v[66:69], v[186:189], v[58:61]
	v_mfma_f32_16x16x32_bf16 v[30:33], v[50:53], v[196:199], v[30:33]
	v_mfma_f32_16x16x32_bf16 v[26:29], v[66:69], v[196:199], v[26:29]
	v_mfma_f32_16x16x32_bf16 v[14:17], v[50:53], v[204:207], v[14:17]
	v_mfma_f32_16x16x32_bf16 v[10:13], v[66:69], v[204:207], v[10:13]
	v_mfma_f32_16x16x32_bf16 v[78:81], v[54:57], v[182:185], v[78:81]
	v_mfma_f32_16x16x32_bf16 v[74:77], v[70:73], v[182:185], v[74:77]
	v_mfma_f32_16x16x32_bf16 v[62:65], v[54:57], v[190:193], v[62:65]
	v_mfma_f32_16x16x32_bf16 v[58:61], v[70:73], v[190:193], v[58:61]
	v_mfma_f32_16x16x32_bf16 v[30:33], v[54:57], v[200:203], v[30:33]
	v_mfma_f32_16x16x32_bf16 v[26:29], v[70:73], v[200:203], v[26:29]
	v_mfma_f32_16x16x32_bf16 v[14:17], v[54:57], v[208:211], v[14:17]
	v_mfma_f32_16x16x32_bf16 v[10:13], v[70:73], v[208:211], v[10:13]
	s_setprio 0
	s_setprio 1
	v_mfma_f32_16x16x32_bf16 v[34:37], v[160:163], v[178:181], v[34:37]
	v_mfma_f32_16x16x32_bf16 v[70:73], v[166:169], v[182:185], v[34:37]
	v_mfma_f32_16x16x32_bf16 v[34:37], v[170:173], v[178:181], v[38:41]
	v_mfma_f32_16x16x32_bf16 v[66:69], v[174:177], v[182:185], v[34:37]
	v_mfma_f32_16x16x32_bf16 v[34:37], v[160:163], v[186:189], v[46:49]
	v_mfma_f32_16x16x32_bf16 v[46:49], v[166:169], v[190:193], v[34:37]
	v_mfma_f32_16x16x32_bf16 v[34:37], v[170:173], v[186:189], v[42:45]
	v_mfma_f32_16x16x32_bf16 v[22:25], v[160:163], v[196:199], v[22:25]
	v_mfma_f32_16x16x32_bf16 v[18:21], v[170:173], v[196:199], v[18:21]
	v_mfma_f32_16x16x32_bf16 v[6:9], v[160:163], v[204:207], v[6:9]
	v_mfma_f32_16x16x32_bf16 v[2:5], v[170:173], v[204:207], v[2:5]
	v_mfma_f32_16x16x32_bf16 v[42:45], v[174:177], v[190:193], v[34:37]
	v_mfma_f32_16x16x32_bf16 v[22:25], v[166:169], v[200:203], v[22:25]
	v_mfma_f32_16x16x32_bf16 v[18:21], v[174:177], v[200:203], v[18:21]
	v_mfma_f32_16x16x32_bf16 v[6:9], v[166:169], v[208:211], v[6:9]
	v_mfma_f32_16x16x32_bf16 v[2:5], v[174:177], v[208:211], v[2:5]
	s_setprio 0
	s_barrier
	s_add_i32 s19, s19, 2
	s_add_u32 s38, s38, 0x100
	s_addc_u32 s39, s39, 0
	s_add_u32 s16, s16, 0x100
	s_addc_u32 s17, s17, 0
	s_cmp_gt_u32 s19, 29
	s_cbranch_scc0 .LBB0_89
	s_and_b64 vcc, exec, s[12:13]
	s_cbranch_vccz .LBB0_92
	s_barrier

; #define PG8_STAGE(bufoff, gbase, voff) do { _Pragma("unroll") for (int _i = 0; _i < 2; ++_i) \
;         __builtin_amdgcn_global_load_lds((const unsigned*)((const char*)(gbase) + (voff)[_i]), (PG8_LAS unsigned*)(lds + (bufoff) + ldsw + _i * 8192), 16, 0, 0); } while (0)
; #define PG8_WAIT_V(n) asm volatile("s_waitcnt vmcnt(" #n ")" ::: "memory")
; #define PG8_BAR __builtin_amdgcn_s_barrier()
;     __device__ __forceinline__ void operator()(const f32x4 (&acc)[2][2][4][2], const Unit& u, int wr, int wc, int fr, int fq) const {
;     ...
;         const unsigned toff = (unsigned)(((wr * 4 + wc) * 64 + fq * 16 + fr) * 16);
;         const __amdgpu_buffer_rsrc_t rs = __builtin_amdgcn_make_buffer_rsrc(slot, 0, 393216, 0x00020000);
;         const int colu = u.pn * BM + wc * 32;
; template <class Epi, class Sched, bool ALIGN_EPI = false, bool SP2 = false>
; __device__ __forceinline__ void gemm_phase(PG8_LAS unsigned char* lds, const Sched& S, const Epi& E, int wave_id) {
;     ...
;         PG8_STAGE(PG8_SB(1, 0), cB + kstep, voffB); PG8_STAGE(PG8_SA(1, 0), cA + kstep, voffA); PG8_STAGE(PG8_SB(1, 1), cB + hstep + kstep, voffB);
;         PG8_WAIT_V(6); PG8_BAR;
.LBB0_830:
	s_add_u32 s35, s12, 0x10200000
	s_addc_u32 s61, s13, 0
	s_add_u32 s70, s4, 0x2d00000
	s_addc_u32 s71, s16, 0
	v_readlane_b32 s4, v252, 3
	s_add_u32 s72, s12, 0x20800000
	s_mul_i32 s30, s4, 0x1800
	s_addc_u32 s73, s13, 0
	s_lshl_b64 s[20:21], s[30:31], 2
	s_add_u32 s4, s12, s20
	s_addc_u32 s16, s13, s21
	s_add_u32 s60, s4, 0x10a800
	s_addc_u32 s20, s16, 0
	s_mul_i32 s4, s2, 0x60000
	s_add_u32 s4, s12, s4
	s_mul_hi_i32 s12, s2, 0x60000
	s_addc_u32 s12, s13, s12
	v_bfe_u32 v18, v16, 4, 2
	s_add_u32 s52, s4, 0x28800000
	v_and_b32_e32 v17, 15, v16
	v_lshlrev_b32_e32 v19, 4, v18
	v_lshlrev_b32_e32 v16, 2, v16
	s_addc_u32 s19, s12, 0
	s_and_b32 s28, s17, 3
	v_lshl_or_b32 v20, v17, 6, v19
	s_lshl_b32 s4, s18, 13
	v_and_b32_e32 v16, 32, v16
	v_bitop3_b32 v21, v20, s4, v16 bitop3:0xde
	s_lshl_b32 s4, s28, 12
	s_add_i32 m0, s23, 0x18000
	v_lshl_add_u64 v[8:9], v[8:9], 0, s[26:27]
	s_lshl_b32 s21, s18, 6
	s_lshl_b32 s16, s28, 5
	v_bitop3_b32 v194, v20, s4, v16 bitop3:0xde
	s_waitcnt vmcnt(2)
	s_barrier
	global_load_lds_dwordx4 v[8:9], off
	v_lshl_add_u64 v[6:7], v[6:7], 0, s[26:27]
	s_add_i32 m0, s23, 0x1a000
	s_add_i32 s17, s23, 0x8000
	s_add_i32 s4, s23, 0xa000
	global_load_lds_dwordx4 v[6:7], off
	v_lshl_add_u64 v[2:3], v[2:3], 0, s[26:27]
	s_mov_b32 m0, s17
	s_add_u32 s12, s40, 0x80080
	global_load_lds_dwordx4 v[2:3], off
	v_lshl_add_u64 v[2:3], v[4:5], 0, s[26:27]
	s_mov_b32 m0, s4
	s_addc_u32 s13, s41, 0
	global_load_lds_dwordx4 v[2:3], off
	s_add_i32 m0, s23, 0x1c000
	v_lshl_add_u64 v[2:3], s[12:13], 0, v[0:1]
	global_load_lds_dwordx4 v[2:3], off
	v_lshl_add_u64 v[2:3], s[12:13], 0, v[200:201]
	s_add_i32 m0, s23, 0x1e000
	s_cmpk_lt_u32 s5, 0x100
	global_load_lds_dwordx4 v[2:3], off
	s_cselect_b64 s[12:13], -1, 0
	s_and_b32 s5, s5, 0xfffff00
	s_lshl_b32 s18, s28, 6
	s_or_b32 s5, s18, s5
	v_or3_b32 v2, s5, v19, v17
	v_lshlrev_b32_e32 v243, 4, v2
	v_lshlrev_b32_e32 v2, 15, v10
	v_and_b32_e32 v2, 0xffff0000, v2
	v_lshl_add_u32 v2, v11, 12, v2
	v_and_b32_e32 v3, 1, v10
	v_lshl_or_b32 v2, v3, 6, v2
	v_lshl_add_u32 v206, v12, 1, v2
	v_lshlrev_b32_e32 v2, 15, v13
	v_and_b32_e32 v2, 0xffff0000, v2
	s_waitcnt vmcnt(0)
	v_lshl_add_u32 v2, v14, 12, v2
	v_and_b32_e32 v3, 1, v13
	v_lshl_or_b32 v2, v3, 6, v2
	s_mov_b32 s50, 32
	v_lshl_or_b32 v202, v17, 12, v19
	v_mov_b32_e32 v203, v1
	s_or_b32 s5, s21, 16
	s_or_b32 s74, s21, 32
	s_or_b32 s75, s21, 48
	v_lshlrev_b32_e32 v204, 5, v18
	v_mov_b32_e32 v205, v1
	s_and_b32 s53, s19, 0xffff
	v_mov_b32_e32 v207, v1
	v_lshl_add_u32 v208, v15, 1, v2
	v_mov_b32_e32 v209, v1
	s_mov_b32 s51, 0
	v_add_u32_e32 v244, 0, v21
	s_mov_b32 s30, 0
	s_mov_b64 s[42:43], s[40:41]
	s_mov_b64 s[36:37], s[44:45]
	s_barrier
	s_branch .LBB0_833

; #define PG8_STAGE(bufoff, gbase, voff) do { _Pragma("unroll") for (int _i = 0; _i < 2; ++_i) \
;         __builtin_amdgcn_global_load_lds((const unsigned*)((const char*)(gbase) + (voff)[_i]), (PG8_LAS unsigned*)(lds + (bufoff) + ldsw + _i * 8192), 16, 0, 0); } while (0)
; #define PG8_LDA(dst, b, h) do { _Pragma("unroll") for (int m = 0; m < 4; ++m) _Pragma("unroll") for (int k = 0; k < 2; ++k) dst[m][k] = *(const PG8_LAS bf16x8*)(lds + PG8_SA(b, h) + aoff + m * 2048 + k * 1024); } while (0)
; #define PG8_LDB(dst, b, h) do { _Pragma("unroll") for (int n = 0; n < 2; ++n) _Pragma("unroll") for (int k = 0; k < 2; ++k) dst[n][k] = *(const PG8_LAS bf16x8*)(lds + PG8_SB(b, h) + boff + n * 2048 + k * 1024); } while (0)
; #define PG8_MMA(ai, bj, At, Bt) do { __builtin_amdgcn_s_setprio(1); _Pragma("unroll") for (int m = 0; m < 4; ++m) _Pragma("unroll") for (int n = 0; n < 2; ++n) _Pragma("unroll") for (int k = 0; k < 2; ++k) \
;         acc[ai][bj][m][n] = __builtin_amdgcn_mfma_f32_16x16x32_bf16(Bt[n][k], At[m][k], acc[ai][bj][m][n], 0, 0, 0); __builtin_amdgcn_s_setprio(0); } while (0)
; #define PG8_WAIT_V(n) asm volatile("s_waitcnt vmcnt(" #n ")" ::: "memory")
; #define PG8_BAR __builtin_amdgcn_s_barrier()
; template <class Epi, class Sched, bool ALIGN_EPI = false, bool SP2 = false>
; __device__ __forceinline__ void gemm_phase(PG8_LAS unsigned char* lds, const Sched& S, const Epi& E, int wave_id) {
;     ...
;         for (int t = 0; t < nt; t += 2) {
;             const bool last = (t == nt - 2);
;             const char* a1 = cA + (size_t)(t + 1) * kstep;
;             const char* a2 = last ? nA : cA + (size_t)(t + 2) * kstep; const char* b2 = last ? nB : cB + (size_t)(t + 2) * kstep;
;             const char* a3 = a2 + kstep; const char* b3 = b2 + kstep;
;             if (last && has_next) S.a_ready(nxt);
;             if constexpr (SP2) {
;             PG8_LDB(B0, 0, 0); PG8_LDB(B1, 0, 1); PG8_SCHED; PG8_LDA(At, 0, 0); PG8_STAGE(PG8_SA(1, 1), a1 + hstep, voffA);
;             PG8_WAIT_V(8); PG8_WAIT_L(0); PG8_BAR; PG8_MMA(0, 0, At, B0); PG8_MMA(0, 1, At, B1); PG8_BAR; PG8_SCHED;
;             PG8_LDA(At, 0, 1); PG8_STAGE(PG8_SB(0, 0), b2, voffB); PG8_STAGE(PG8_SB(0, 1), b2 + hstep, voffB); PG8_STAGE(PG8_SA(0, 0), a2, voffA);
;             PG8_WAIT_V(8); PG8_WAIT_L(0); PG8_BAR; PG8_MMA(1, 0, At, B0); PG8_MMA(1, 1, At, B1); PG8_BAR; PG8_SCHED;
.LBB0_839:
	s_add_i32 s66, s40, 2
	s_add_u32 s41, s38, 0xfff80080
	s_addc_u32 s44, s39, -1
	s_add_i32 s67, 0, 0x10000
	s_cmp_eq_u32 s30, s40
	s_cselect_b32 s45, s37, s44
	s_cselect_b32 s44, s36, s41
	s_cselect_b32 s41, s43, s47
	s_cselect_b32 s40, s42, s46
	s_add_i32 s79, 0, 0x14000
	v_add_u32_e32 v142, s67, v194
	v_add_u32_e32 v158, s79, v194
	ds_read_b128 v[130:133], v142
	ds_read_b128 v[134:137], v142 offset:1024
	ds_read_b128 v[138:141], v142 offset:2048
	ds_read_b128 v[142:145], v142 offset:3072
	ds_read_b128 v[146:149], v158
	ds_read_b128 v[150:153], v158 offset:1024
	ds_read_b128 v[154:157], v158 offset:2048
	ds_read_b128 v[158:161], v158 offset:3072
	s_add_i32 m0, s23, 0xc000
	ds_read_b128 v[162:165], v244
	ds_read_b128 v[166:169], v244 offset:1024
	ds_read_b128 v[170:173], v244 offset:2048
	ds_read_b128 v[174:177], v244 offset:3072
	ds_read_b128 v[178:181], v244 offset:4096
	ds_read_b128 v[182:185], v244 offset:5120
	ds_read_b128 v[186:189], v244 offset:6144
	ds_read_b128 v[190:193], v244 offset:7168
	global_load_lds_dwordx4 v206, s[38:39]
	s_add_i32 m0, s23, 0xe000
	s_nop 0
	global_load_lds_dwordx4 v208, s[38:39]
	s_cmp_eq_u32 s66, 2
	s_cbranch_scc1 .Lfiw_1_0
	s_waitcnt vmcnt(8)
.Lfiw_1_0:
	s_waitcnt lgkmcnt(0)
	s_barrier
	s_setprio 1
	s_waitcnt lgkmcnt(0)
	v_mfma_f32_16x16x32_bf16 v[126:129], v[130:133], v[162:165], v[126:129]
	v_mfma_f32_16x16x32_bf16 v[122:125], v[138:141], v[162:165], v[122:125]
	v_mfma_f32_16x16x32_bf16 v[110:113], v[130:133], v[170:173], v[110:113]
	v_mfma_f32_16x16x32_bf16 v[106:109], v[138:141], v[170:173], v[106:109]
	v_mfma_f32_16x16x32_bf16 v[94:97], v[130:133], v[178:181], v[94:97]
	v_mfma_f32_16x16x32_bf16 v[90:93], v[138:141], v[178:181], v[90:93]
	v_mfma_f32_16x16x32_bf16 v[78:81], v[130:133], v[186:189], v[78:81]
	v_mfma_f32_16x16x32_bf16 v[74:77], v[138:141], v[186:189], v[74:77]
	v_mfma_f32_16x16x32_bf16 v[126:129], v[134:137], v[166:169], v[126:129]
	v_mfma_f32_16x16x32_bf16 v[122:125], v[142:145], v[166:169], v[122:125]
	v_mfma_f32_16x16x32_bf16 v[110:113], v[134:137], v[174:177], v[110:113]
	v_mfma_f32_16x16x32_bf16 v[106:109], v[142:145], v[174:177], v[106:109]
	v_mfma_f32_16x16x32_bf16 v[94:97], v[134:137], v[182:185], v[94:97]
	v_mfma_f32_16x16x32_bf16 v[90:93], v[142:145], v[182:185], v[90:93]
	v_mfma_f32_16x16x32_bf16 v[78:81], v[134:137], v[190:193], v[78:81]
	v_mfma_f32_16x16x32_bf16 v[74:77], v[142:145], v[190:193], v[74:77]
	s_setprio 0
	s_setprio 1
	v_mfma_f32_16x16x32_bf16 v[118:121], v[146:149], v[162:165], v[118:121]
	v_mfma_f32_16x16x32_bf16 v[114:117], v[154:157], v[162:165], v[114:117]
	v_mfma_f32_16x16x32_bf16 v[102:105], v[146:149], v[170:173], v[102:105]
	v_mfma_f32_16x16x32_bf16 v[98:101], v[154:157], v[170:173], v[98:101]
	v_mfma_f32_16x16x32_bf16 v[86:89], v[146:149], v[178:181], v[86:89]
	v_mfma_f32_16x16x32_bf16 v[82:85], v[154:157], v[178:181], v[82:85]
	v_mfma_f32_16x16x32_bf16 v[70:73], v[146:149], v[186:189], v[70:73]
	v_mfma_f32_16x16x32_bf16 v[66:69], v[154:157], v[186:189], v[66:69]
	v_mfma_f32_16x16x32_bf16 v[118:121], v[150:153], v[166:169], v[118:121]
	v_mfma_f32_16x16x32_bf16 v[114:117], v[158:161], v[166:169], v[114:117]
	v_mfma_f32_16x16x32_bf16 v[102:105], v[150:153], v[174:177], v[102:105]
	v_mfma_f32_16x16x32_bf16 v[98:101], v[158:161], v[174:177], v[98:101]
	v_mfma_f32_16x16x32_bf16 v[86:89], v[150:153], v[182:185], v[86:89]
	v_mfma_f32_16x16x32_bf16 v[82:85], v[158:161], v[182:185], v[82:85]
	v_mfma_f32_16x16x32_bf16 v[70:73], v[150:153], v[190:193], v[70:73]
	v_mfma_f32_16x16x32_bf16 v[66:69], v[158:161], v[190:193], v[66:69]
	s_setprio 0
	s_barrier
	s_add_i32 s67, s67, s22
	s_mov_b32 m0, s67
	ds_read_b128 v[162:165], v244 offset:16384
	ds_read_b128 v[166:169], v244 offset:17408
	ds_read_b128 v[170:173], v244 offset:18432
	ds_read_b128 v[174:177], v244 offset:19456
	ds_read_b128 v[178:181], v244 offset:20480
	ds_read_b128 v[182:185], v244 offset:21504
	ds_read_b128 v[186:189], v244 offset:22528
	ds_read_b128 v[190:193], v244 offset:23552
	global_load_lds_dwordx4 v0, s[40:41]
	s_add_i32 m0, s67, 0x2000
	s_add_u32 vcc_lo, s40, 0x80000
	s_addc_u32 vcc_hi, s41, 0
	s_add_i32 s67, s79, s22
	global_load_lds_dwordx4 v200, s[40:41]
	s_mov_b32 m0, s67
	s_nop 0
	global_load_lds_dwordx4 v0, vcc
	s_add_i32 m0, s67, 0x2000
	s_nop 0
	global_load_lds_dwordx4 v200, vcc
	s_mov_b32 m0, s23
	s_nop 0
	global_load_lds_dwordx4 v196, s[44:45]
	s_mov_b32 m0, s24
	s_nop 0
	global_load_lds_dwordx4 v198, s[44:45]
	s_cmp_eq_u32 s66, 2
	s_cbranch_scc1 .Lfiw_1_1
	s_waitcnt vmcnt(8)
; #define PG8_STAGE(bufoff, gbase, voff) do { _Pragma("unroll") for (int _i = 0; _i < 2; ++_i) \
;         __builtin_amdgcn_global_load_lds((const unsigned*)((const char*)(gbase) + (voff)[_i]), (PG8_LAS unsigned*)(lds + (bufoff) + ldsw + _i * 8192), 16, 0, 0); } while (0)
; #define PG8_LDA(dst, b, h) do { _Pragma("unroll") for (int m = 0; m < 4; ++m) _Pragma("unroll") for (int k = 0; k < 2; ++k) dst[m][k] = *(const PG8_LAS bf16x8*)(lds + PG8_SA(b, h) + aoff + m * 2048 + k * 1024); } while (0)
; #define PG8_LDB(dst, b, h) do { _Pragma("unroll") for (int n = 0; n < 2; ++n) _Pragma("unroll") for (int k = 0; k < 2; ++k) dst[n][k] = *(const PG8_LAS bf16x8*)(lds + PG8_SB(b, h) + boff + n * 2048 + k * 1024); } while (0)
; #define PG8_MMA(ai, bj, At, Bt) do { __builtin_amdgcn_s_setprio(1); _Pragma("unroll") for (int m = 0; m < 4; ++m) _Pragma("unroll") for (int n = 0; n < 2; ++n) _Pragma("unroll") for (int k = 0; k < 2; ++k) \
;         acc[ai][bj][m][n] = __builtin_amdgcn_mfma_f32_16x16x32_bf16(Bt[n][k], At[m][k], acc[ai][bj][m][n], 0, 0, 0); __builtin_amdgcn_s_setprio(0); } while (0)
; #define PG8_WAIT_V(n) asm volatile("s_waitcnt vmcnt(" #n ")" ::: "memory")
; #define PG8_WAIT_L(n) asm volatile("s_waitcnt lgkmcnt(" #n ")" ::: "memory")
; #define PG8_BAR __builtin_amdgcn_s_barrier()
; #define PG8_SCHED __builtin_amdgcn_sched_barrier(0)
; template <class Epi, class Sched, bool ALIGN_EPI = false, bool SP2 = false>
; __device__ __forceinline__ void gemm_phase(PG8_LAS unsigned char* lds, const Sched& S, const Epi& E, int wave_id) {
;     ...
;             PG8_WAIT_V(8); PG8_WAIT_L(0); PG8_BAR; PG8_MMA(1, 0, At, B0); PG8_MMA(1, 1, At, B1); PG8_BAR; PG8_SCHED;
;             PG8_LDB(B0, 1, 0); PG8_LDB(B1, 1, 1); PG8_SCHED; PG8_LDA(At, 1, 0); PG8_STAGE(PG8_SA(0, 1), a2 + hstep, voffA);
;             PG8_WAIT_V(8); PG8_WAIT_L(0); PG8_BAR; PG8_MMA(0, 0, At, B0); PG8_MMA(0, 1, At, B1); PG8_BAR; PG8_SCHED;
.Lfiw_1_1:
	s_waitcnt lgkmcnt(0)
	s_barrier
	s_setprio 1
	s_waitcnt lgkmcnt(0)
	v_mfma_f32_16x16x32_bf16 v[62:65], v[130:133], v[162:165], v[62:65]
	v_mfma_f32_16x16x32_bf16 v[58:61], v[138:141], v[162:165], v[58:61]
	v_mfma_f32_16x16x32_bf16 v[46:49], v[130:133], v[170:173], v[46:49]
	v_mfma_f32_16x16x32_bf16 v[42:45], v[138:141], v[170:173], v[42:45]
	v_mfma_f32_16x16x32_bf16 v[30:33], v[130:133], v[178:181], v[30:33]
	v_mfma_f32_16x16x32_bf16 v[26:29], v[138:141], v[178:181], v[26:29]
	v_mfma_f32_16x16x32_bf16 v[14:17], v[130:133], v[186:189], v[14:17]
	v_mfma_f32_16x16x32_bf16 v[10:13], v[138:141], v[186:189], v[10:13]
	v_mfma_f32_16x16x32_bf16 v[62:65], v[134:137], v[166:169], v[62:65]
	v_mfma_f32_16x16x32_bf16 v[58:61], v[142:145], v[166:169], v[58:61]
	v_mfma_f32_16x16x32_bf16 v[46:49], v[134:137], v[174:177], v[46:49]
	v_mfma_f32_16x16x32_bf16 v[42:45], v[142:145], v[174:177], v[42:45]
	v_mfma_f32_16x16x32_bf16 v[30:33], v[134:137], v[182:185], v[30:33]
	v_mfma_f32_16x16x32_bf16 v[26:29], v[142:145], v[182:185], v[26:29]
	v_mfma_f32_16x16x32_bf16 v[14:17], v[134:137], v[190:193], v[14:17]
	v_mfma_f32_16x16x32_bf16 v[10:13], v[142:145], v[190:193], v[10:13]
	s_setprio 0
	s_setprio 1
	v_mfma_f32_16x16x32_bf16 v[54:57], v[146:149], v[162:165], v[54:57]
	v_mfma_f32_16x16x32_bf16 v[50:53], v[154:157], v[162:165], v[50:53]
	v_mfma_f32_16x16x32_bf16 v[38:41], v[146:149], v[170:173], v[38:41]
	v_mfma_f32_16x16x32_bf16 v[34:37], v[154:157], v[170:173], v[34:37]
	v_mfma_f32_16x16x32_bf16 v[22:25], v[146:149], v[178:181], v[22:25]
	v_mfma_f32_16x16x32_bf16 v[18:21], v[154:157], v[178:181], v[18:21]
	v_mfma_f32_16x16x32_bf16 v[6:9], v[146:149], v[186:189], v[6:9]
	v_mfma_f32_16x16x32_bf16 v[2:5], v[154:157], v[186:189], v[2:5]
	v_mfma_f32_16x16x32_bf16 v[54:57], v[150:153], v[166:169], v[54:57]
	v_mfma_f32_16x16x32_bf16 v[50:53], v[158:161], v[166:169], v[50:53]
	v_mfma_f32_16x16x32_bf16 v[38:41], v[150:153], v[174:177], v[38:41]
	v_mfma_f32_16x16x32_bf16 v[34:37], v[158:161], v[174:177], v[34:37]
	v_mfma_f32_16x16x32_bf16 v[22:25], v[150:153], v[182:185], v[22:25]
	v_mfma_f32_16x16x32_bf16 v[18:21], v[158:161], v[182:185], v[18:21]
	v_mfma_f32_16x16x32_bf16 v[6:9], v[150:153], v[190:193], v[6:9]
	v_mfma_f32_16x16x32_bf16 v[2:5], v[158:161], v[190:193], v[2:5]
	s_setprio 0
	s_barrier
	s_add_i32 s67, 0, 0x18000
	s_add_i32 s79, 0, 0x1c000
	v_add_u32_e32 v142, s67, v194
	v_add_u32_e32 v158, s79, v194
	ds_read_b128 v[130:133], v142
	ds_read_b128 v[134:137], v142 offset:1024
	ds_read_b128 v[138:141], v142 offset:2048
	ds_read_b128 v[142:145], v142 offset:3072
	ds_read_b128 v[146:149], v158
	ds_read_b128 v[150:153], v158 offset:1024
	ds_read_b128 v[154:157], v158 offset:2048
	ds_read_b128 v[158:161], v158 offset:3072
	s_add_u32 s98, s44, 0x80000
	s_addc_u32 s99, s45, 0
	s_mov_b32 m0, s25
	ds_read_b128 v[162:165], v244 offset:32768
	ds_read_b128 v[166:169], v244 offset:33792
	ds_read_b128 v[170:173], v244 offset:34816
	ds_read_b128 v[174:177], v244 offset:35840
	ds_read_b128 v[178:181], v244 offset:36864
	ds_read_b128 v[182:185], v244 offset:37888
	ds_read_b128 v[186:189], v244 offset:38912
	ds_read_b128 v[190:193], v244 offset:39936
	global_load_lds_dwordx4 v196, s[98:99]
	s_mov_b32 m0, s33
	s_nop 0
	global_load_lds_dwordx4 v198, s[98:99]
	s_waitcnt vmcnt(8)
	s_waitcnt lgkmcnt(0)
	s_barrier
	s_setprio 1
	s_waitcnt lgkmcnt(0)
	v_mfma_f32_16x16x32_bf16 v[126:129], v[130:133], v[162:165], v[126:129]
	v_mfma_f32_16x16x32_bf16 v[122:125], v[138:141], v[162:165], v[122:125]
	v_mfma_f32_16x16x32_bf16 v[110:113], v[130:133], v[170:173], v[110:113]
	v_mfma_f32_16x16x32_bf16 v[106:109], v[138:141], v[170:173], v[106:109]
	v_mfma_f32_16x16x32_bf16 v[94:97], v[130:133], v[178:181], v[94:97]
	v_mfma_f32_16x16x32_bf16 v[90:93], v[138:141], v[178:181], v[90:93]
	v_mfma_f32_16x16x32_bf16 v[78:81], v[130:133], v[186:189], v[78:81]
	v_mfma_f32_16x16x32_bf16 v[74:77], v[138:141], v[186:189], v[74:77]
	v_mfma_f32_16x16x32_bf16 v[126:129], v[134:137], v[166:169], v[126:129]
	v_mfma_f32_16x16x32_bf16 v[122:125], v[142:145], v[166:169], v[122:125]
	v_mfma_f32_16x16x32_bf16 v[110:113], v[134:137], v[174:177], v[110:113]
	v_mfma_f32_16x16x32_bf16 v[106:109], v[142:145], v[174:177], v[106:109]
	v_mfma_f32_16x16x32_bf16 v[94:97], v[134:137], v[182:185], v[94:97]
	v_mfma_f32_16x16x32_bf16 v[90:93], v[142:145], v[182:185], v[90:93]
	v_mfma_f32_16x16x32_bf16 v[78:81], v[134:137], v[190:193], v[78:81]
	v_mfma_f32_16x16x32_bf16 v[74:77], v[142:145], v[190:193], v[74:77]
	s_setprio 0
	s_setprio 1
	v_mfma_f32_16x16x32_bf16 v[118:121], v[146:149], v[162:165], v[118:121]
	v_mfma_f32_16x16x32_bf16 v[114:117], v[154:157], v[162:165], v[114:117]
	v_mfma_f32_16x16x32_bf16 v[102:105], v[146:149], v[170:173], v[102:105]
	v_mfma_f32_16x16x32_bf16 v[98:101], v[154:157], v[170:173], v[98:101]
	v_mfma_f32_16x16x32_bf16 v[86:89], v[146:149], v[178:181], v[86:89]
	v_mfma_f32_16x16x32_bf16 v[82:85], v[154:157], v[178:181], v[82:85]
	v_mfma_f32_16x16x32_bf16 v[70:73], v[146:149], v[186:189], v[70:73]
	v_mfma_f32_16x16x32_bf16 v[66:69], v[154:157], v[186:189], v[66:69]
	v_mfma_f32_16x16x32_bf16 v[118:121], v[150:153], v[166:169], v[118:121]
	v_mfma_f32_16x16x32_bf16 v[114:117], v[158:161], v[166:169], v[114:117]
	v_mfma_f32_16x16x32_bf16 v[102:105], v[150:153], v[174:177], v[102:105]
	v_mfma_f32_16x16x32_bf16 v[98:101], v[158:161], v[174:177], v[98:101]
	v_mfma_f32_16x16x32_bf16 v[86:89], v[150:153], v[182:185], v[86:89]
	v_mfma_f32_16x16x32_bf16 v[82:85], v[158:161], v[182:185], v[82:85]
	v_mfma_f32_16x16x32_bf16 v[70:73], v[150:153], v[190:193], v[70:73]
	v_mfma_f32_16x16x32_bf16 v[66:69], v[158:161], v[190:193], v[66:69]
	s_setprio 0
	s_barrier
; #define PG8_STAGE(bufoff, gbase, voff) do { _Pragma("unroll") for (int _i = 0; _i < 2; ++_i) \
;         __builtin_amdgcn_global_load_lds((const unsigned*)((const char*)(gbase) + (voff)[_i]), (PG8_LAS unsigned*)(lds + (bufoff) + ldsw + _i * 8192), 16, 0, 0); } while (0)
; #define PG8_LDA(dst, b, h) do { _Pragma("unroll") for (int m = 0; m < 4; ++m) _Pragma("unroll") for (int k = 0; k < 2; ++k) dst[m][k] = *(const PG8_LAS bf16x8*)(lds + PG8_SA(b, h) + aoff + m * 2048 + k * 1024); } while (0)
; #define PG8_MMA(ai, bj, At, Bt) do { __builtin_amdgcn_s_setprio(1); _Pragma("unroll") for (int m = 0; m < 4; ++m) _Pragma("unroll") for (int n = 0; n < 2; ++n) _Pragma("unroll") for (int k = 0; k < 2; ++k) \
;         acc[ai][bj][m][n] = __builtin_amdgcn_mfma_f32_16x16x32_bf16(Bt[n][k], At[m][k], acc[ai][bj][m][n], 0, 0, 0); __builtin_amdgcn_s_setprio(0); } while (0)
; #define PG8_WAIT_V(n) asm volatile("s_waitcnt vmcnt(" #n ")" ::: "memory")
; #define PG8_WAIT_L(n) asm volatile("s_waitcnt lgkmcnt(" #n ")" ::: "memory")
; #define PG8_BAR __builtin_amdgcn_s_barrier()
; #define PG8_SCHED __builtin_amdgcn_sched_barrier(0)
; template <class Epi, class Sched, bool ALIGN_EPI = false, bool SP2 = false>
; __device__ __forceinline__ void gemm_phase(PG8_LAS unsigned char* lds, const Sched& S, const Epi& E, int wave_id) {
;     ...
;             PG8_LDA(At, 1, 1); PG8_STAGE(PG8_SB(1, 0), b3, voffB); PG8_STAGE(PG8_SB(1, 1), b3 + hstep, voffB); PG8_STAGE(PG8_SA(1, 0), a3, voffA);
;             PG8_WAIT_V(8); PG8_WAIT_L(0); PG8_BAR; PG8_MMA(1, 0, At, B0); PG8_MMA(1, 1, At, B1); PG8_BAR; PG8_SCHED;
	s_add_i32 s100, s67, s22
	s_sub_i32 m0, s100, 0x80
	ds_read_b128 v[162:165], v244 offset:49152
	ds_read_b128 v[166:169], v244 offset:50176
	ds_read_b128 v[170:173], v244 offset:51200
	ds_read_b128 v[174:177], v244 offset:52224
	ds_read_b128 v[178:181], v244 offset:53248
	ds_read_b128 v[182:185], v244 offset:54272
	ds_read_b128 v[186:189], v244 offset:55296
	ds_read_b128 v[190:193], v244 offset:56320
	global_load_lds_dwordx4 v0, s[40:41] offset:128
	s_add_i32 m0, s100, 0x1f80
	s_add_i32 s100, s79, s22
	global_load_lds_dwordx4 v200, s[40:41] offset:128
	s_add_u32 s40, s40, 0x80080
	s_addc_u32 s41, s41, 0
	s_mov_b32 m0, s100
	s_nop 0
	global_load_lds_dwordx4 v0, s[40:41]
	s_add_i32 m0, s100, 0x2000
	s_nop 0
	global_load_lds_dwordx4 v200, s[40:41]
	s_sub_i32 m0, s17, 0x80
	s_nop 0
	global_load_lds_dwordx4 v196, s[44:45] offset:128
	s_sub_i32 m0, s4, 0x80
	s_nop 0
	global_load_lds_dwordx4 v198, s[44:45] offset:128
	s_waitcnt vmcnt(8)
	s_waitcnt lgkmcnt(0)
	s_barrier
	s_setprio 1
	s_waitcnt lgkmcnt(0)
	v_mfma_f32_16x16x32_bf16 v[62:65], v[130:133], v[162:165], v[62:65]
	v_mfma_f32_16x16x32_bf16 v[58:61], v[138:141], v[162:165], v[58:61]
	v_mfma_f32_16x16x32_bf16 v[46:49], v[130:133], v[170:173], v[46:49]
	v_mfma_f32_16x16x32_bf16 v[42:45], v[138:141], v[170:173], v[42:45]
	v_mfma_f32_16x16x32_bf16 v[30:33], v[130:133], v[178:181], v[30:33]
	v_mfma_f32_16x16x32_bf16 v[26:29], v[138:141], v[178:181], v[26:29]
	v_mfma_f32_16x16x32_bf16 v[14:17], v[130:133], v[186:189], v[14:17]
	v_mfma_f32_16x16x32_bf16 v[10:13], v[138:141], v[186:189], v[10:13]
	v_mfma_f32_16x16x32_bf16 v[62:65], v[134:137], v[166:169], v[62:65]
	v_mfma_f32_16x16x32_bf16 v[58:61], v[142:145], v[166:169], v[58:61]
	v_mfma_f32_16x16x32_bf16 v[46:49], v[134:137], v[174:177], v[46:49]
	v_mfma_f32_16x16x32_bf16 v[42:45], v[142:145], v[174:177], v[42:45]
	v_mfma_f32_16x16x32_bf16 v[30:33], v[134:137], v[182:185], v[30:33]
	v_mfma_f32_16x16x32_bf16 v[26:29], v[142:145], v[182:185], v[26:29]
	v_mfma_f32_16x16x32_bf16 v[14:17], v[134:137], v[190:193], v[14:17]
	v_mfma_f32_16x16x32_bf16 v[10:13], v[142:145], v[190:193], v[10:13]
	s_setprio 0
	s_setprio 1
	v_mfma_f32_16x16x32_bf16 v[54:57], v[146:149], v[162:165], v[54:57]
	v_mfma_f32_16x16x32_bf16 v[50:53], v[154:157], v[162:165], v[50:53]
	v_mfma_f32_16x16x32_bf16 v[38:41], v[146:149], v[170:173], v[38:41]
	v_mfma_f32_16x16x32_bf16 v[34:37], v[154:157], v[170:173], v[34:37]
	v_mfma_f32_16x16x32_bf16 v[22:25], v[146:149], v[178:181], v[22:25]
	v_mfma_f32_16x16x32_bf16 v[18:21], v[154:157], v[178:181], v[18:21]
	v_mfma_f32_16x16x32_bf16 v[6:9], v[146:149], v[186:189], v[6:9]
	v_mfma_f32_16x16x32_bf16 v[2:5], v[154:157], v[186:189], v[2:5]
	v_mfma_f32_16x16x32_bf16 v[54:57], v[150:153], v[166:169], v[54:57]
	v_mfma_f32_16x16x32_bf16 v[50:53], v[158:161], v[166:169], v[50:53]
	v_mfma_f32_16x16x32_bf16 v[38:41], v[150:153], v[174:177], v[38:41]
	v_mfma_f32_16x16x32_bf16 v[34:37], v[158:161], v[174:177], v[34:37]
	v_mfma_f32_16x16x32_bf16 v[22:25], v[150:153], v[182:185], v[22:25]
	v_mfma_f32_16x16x32_bf16 v[18:21], v[158:161], v[182:185], v[18:21]
	v_mfma_f32_16x16x32_bf16 v[6:9], v[150:153], v[190:193], v[6:9]
	v_mfma_f32_16x16x32_bf16 v[2:5], v[158:161], v[190:193], v[2:5]
	s_setprio 0
	s_barrier
	s_add_u32 s38, s38, 0x100
	s_addc_u32 s39, s39, 0
	s_add_u32 s46, s46, 0x100
	s_addc_u32 s47, s47, 0
	s_cmp_ge_i32 s66, s50
	s_mov_b32 s40, s66
	s_cbranch_scc0 .LBB0_839
	s_and_b64 vcc, exec, s[12:13]
	s_cbranch_vccz .LBB0_842
	s_barrier

; #define PG8_STAGE(bufoff, gbase, voff) do { _Pragma("unroll") for (int _i = 0; _i < 2; ++_i) \
;         __builtin_amdgcn_global_load_lds((const unsigned*)((const char*)(gbase) + (voff)[_i]), (PG8_LAS unsigned*)(lds + (bufoff) + ldsw + _i * 8192), 16, 0, 0); } while (0)
; #define PG8_WAIT_V(n) asm volatile("s_waitcnt vmcnt(" #n ")" ::: "memory")
; #define PG8_BAR __builtin_amdgcn_s_barrier()
; template <class Epi, class Sched, bool ALIGN_EPI = false, bool SP2 = false>
; __device__ __forceinline__ void gemm_phase(PG8_LAS unsigned char* lds, const Sched& S, const Epi& E, int wave_id) {
;     ...
;         PG8_STAGE(PG8_SB(1, 0), cB + kstep, voffB); PG8_STAGE(PG8_SA(1, 0), cA + kstep, voffA); PG8_STAGE(PG8_SB(1, 1), cB + hstep + kstep, voffB);
;         PG8_WAIT_V(6); PG8_BAR;
.LBB0_1033:
	v_bfe_u32 v18, v15, 4, 2
	v_and_b32_e32 v17, 15, v15
	v_lshlrev_b32_e32 v19, 4, v18
	v_lshlrev_b32_e32 v15, 2, v15
	s_lshl_b32 s21, s22, 6
	v_lshl_or_b32 v19, v17, 6, v19
	s_lshl_b32 s22, s22, 13
	v_and_b32_e32 v15, 32, v15
	s_lshl_b32 s13, s13, 5
	v_bitop3_b32 v20, v19, s22, v15 bitop3:0xde
	s_and_b32 s22, s13, 0x60
	s_add_i32 m0, s11, 0x18000
	v_lshl_add_u64 v[8:9], v[8:9], 0, s[26:27]
	s_lshl_b32 s13, s22, 7
	s_waitcnt vmcnt(2)
	s_barrier
	global_load_lds_dwordx4 v[8:9], off
	v_lshl_add_u64 v[6:7], v[6:7], 0, s[26:27]
	s_add_i32 m0, s11, 0x1a000
	s_add_i32 s23, s11, 0x8000
	s_add_i32 s24, s11, 0xa000
	global_load_lds_dwordx4 v[6:7], off
	v_lshl_add_u64 v[2:3], v[2:3], 0, s[26:27]
	s_mov_b32 m0, s23
	s_add_u32 s28, s44, 0x80080
	global_load_lds_dwordx4 v[2:3], off
	v_lshl_add_u64 v[2:3], v[4:5], 0, s[26:27]
	s_mov_b32 m0, s24
	s_addc_u32 s29, s45, 0
	global_load_lds_dwordx4 v[2:3], off
	s_add_i32 m0, s11, 0x1c000
	v_lshl_add_u64 v[2:3], s[28:29], 0, v[0:1]
	global_load_lds_dwordx4 v[2:3], off
	v_lshl_add_u64 v[2:3], s[28:29], 0, v[162:163]
	s_add_i32 m0, s11, 0x1e000
	v_readlane_b32 s28, v254, 45
	global_load_lds_dwordx4 v[2:3], off
	v_lshlrev_b32_e32 v2, 13, v17
	v_lshl_or_b32 v168, v18, 5, v2
	v_lshlrev_b32_e32 v2, 15, v14
	v_and_b32_e32 v2, 0xffff0000, v2
	v_lshl_add_u32 v2, v13, 12, v2
	v_and_b32_e32 v3, 1, v14
	v_lshl_or_b32 v2, v3, 6, v2
	v_lshl_add_u32 v172, v16, 1, v2
	v_lshlrev_b32_e32 v2, 15, v10
	v_and_b32_e32 v2, 0xffff0000, v2
	s_waitcnt vmcnt(0)
	v_lshl_add_u32 v2, v11, 12, v2
	v_and_b32_e32 v3, 1, v10
	s_cmpk_lt_u32 s12, 0x100
	v_mov_b32_e32 v169, v1
	v_lshl_or_b32 v2, v3, 6, v2
	v_readlane_b32 s29, v254, 46
	v_bitop3_b32 v178, v19, s13, v15 bitop3:0xde
	s_cselect_b64 s[12:13], -1, 0
	s_waitcnt lgkmcnt(0)
	v_lshl_add_u64 v[170:171], s[18:19], 0, v[168:169]
	s_or_b32 s25, s21, 16
	s_or_b32 s30, s21, 32
	s_or_b32 s33, s21, 48
	v_mov_b32_e32 v173, v1
	v_lshl_add_u32 v174, v12, 1, v2
	v_mov_b32_e32 v175, v1
	s_mov_b32 s35, 0
	v_add_u32_e32 v179, 0, v20
	s_mov_b32 s48, s28
	v_readlane_b32 s49, v254, 28
	s_mov_b64 s[36:37], s[44:45]
	s_mov_b64 s[28:29], s[42:43]
	s_barrier
	s_branch .LBB0_1036

; #define PG8_STAGE(bufoff, gbase, voff) do { _Pragma("unroll") for (int _i = 0; _i < 2; ++_i) \
;         __builtin_amdgcn_global_load_lds((const unsigned*)((const char*)(gbase) + (voff)[_i]), (PG8_LAS unsigned*)(lds + (bufoff) + ldsw + _i * 8192), 16, 0, 0); } while (0)
; #define PG8_LDA(dst, b, h) do { _Pragma("unroll") for (int m = 0; m < 4; ++m) _Pragma("unroll") for (int k = 0; k < 2; ++k) dst[m][k] = *(const PG8_LAS bf16x8*)(lds + PG8_SA(b, h) + aoff + m * 2048 + k * 1024); } while (0)
; #define PG8_LDB(dst, b, h) do { _Pragma("unroll") for (int n = 0; n < 2; ++n) _Pragma("unroll") for (int k = 0; k < 2; ++k) dst[n][k] = *(const PG8_LAS bf16x8*)(lds + PG8_SB(b, h) + boff + n * 2048 + k * 1024); } while (0)
; #define PG8_MMA(ai, bj, At, Bt) do { __builtin_amdgcn_s_setprio(1); _Pragma("unroll") for (int m = 0; m < 4; ++m) _Pragma("unroll") for (int n = 0; n < 2; ++n) _Pragma("unroll") for (int k = 0; k < 2; ++k) \
;         acc[ai][bj][m][n] = __builtin_amdgcn_mfma_f32_16x16x32_bf16(Bt[n][k], At[m][k], acc[ai][bj][m][n], 0, 0, 0); __builtin_amdgcn_s_setprio(0); } while (0)
; #define PG8_WAIT_V(n) asm volatile("s_waitcnt vmcnt(" #n ")" ::: "memory")
; #define PG8_BAR __builtin_amdgcn_s_barrier()
; template <class Epi, class Sched, bool ALIGN_EPI = false, bool SP2 = false>
; __device__ __forceinline__ void gemm_phase(PG8_LAS unsigned char* lds, const Sched& S, const Epi& E, int wave_id) {
;     ...
;         for (int t = 0; t < nt; t += 2) {
;             const bool last = (t == nt - 2);
;             const char* a1 = cA + (size_t)(t + 1) * kstep;
;             const char* a2 = last ? nA : cA + (size_t)(t + 2) * kstep; const char* b2 = last ? nB : cB + (size_t)(t + 2) * kstep;
;             const char* a3 = a2 + kstep; const char* b3 = b2 + kstep;
;             if (last && has_next) S.a_ready(nxt);
;             if constexpr (SP2) {
;             PG8_LDB(B0, 0, 0); PG8_LDB(B1, 0, 1); PG8_SCHED; PG8_LDA(At, 0, 0); PG8_STAGE(PG8_SA(1, 1), a1 + hstep, voffA);
;             PG8_WAIT_V(8); PG8_WAIT_L(0); PG8_BAR; PG8_MMA(0, 0, At, B0); PG8_MMA(0, 1, At, B1); PG8_BAR; PG8_SCHED;
;             PG8_LDA(At, 0, 1); PG8_STAGE(PG8_SB(0, 0), b2, voffB); PG8_STAGE(PG8_SB(0, 1), b2 + hstep, voffB); PG8_STAGE(PG8_SA(0, 0), a2, voffA);
;             PG8_WAIT_V(8); PG8_WAIT_L(0); PG8_BAR; PG8_MMA(1, 0, At, B0); PG8_MMA(1, 1, At, B1); PG8_BAR; PG8_SCHED;
.LBB0_1039:
	s_add_u32 s44, s42, 0xfff80080
	s_addc_u32 s45, s43, -1
	s_add_i32 s53, 0, 0x10000
	s_cmp_eq_u32 s51, 28
	s_cselect_b32 s47, s29, s45
	s_cselect_b32 s46, s28, s44
	s_cselect_b32 s45, s37, s50
	s_cselect_b32 s44, s36, s19
	s_add_i32 s66, 0, 0x14000
	v_add_u32_e32 v142, s53, v178
	v_add_u32_e32 v158, s66, v178
	ds_read_b128 v[130:133], v142
	ds_read_b128 v[134:137], v142 offset:1024
	ds_read_b128 v[138:141], v142 offset:2048
	ds_read_b128 v[142:145], v142 offset:3072
	ds_read_b128 v[146:149], v158
	ds_read_b128 v[150:153], v158 offset:1024
	ds_read_b128 v[154:157], v158 offset:2048
	ds_read_b128 v[158:161], v158 offset:3072
	s_add_i32 m0, s11, 0xc000
	ds_read_b128 v[180:183], v179
	ds_read_b128 v[184:187], v179 offset:1024
	ds_read_b128 v[188:191], v179 offset:2048
	ds_read_b128 v[196:199], v179 offset:3072
	ds_read_b128 v[200:203], v179 offset:4096
	ds_read_b128 v[204:207], v179 offset:5120
	ds_read_b128 v[208:211], v179 offset:6144
	ds_read_b128 v[212:215], v179 offset:7168
	global_load_lds_dwordx4 v172, s[42:43]
	s_add_i32 m0, s11, 0xe000
	s_nop 0
	global_load_lds_dwordx4 v174, s[42:43]
	s_cmp_eq_u32 s51, -2
	s_cbranch_scc1 .Lfiw_2_0
	s_waitcnt vmcnt(8)
.Lfiw_2_0:
	s_waitcnt lgkmcnt(0)
	s_barrier
	s_setprio 1
	s_waitcnt lgkmcnt(0)
	v_mfma_f32_16x16x32_bf16 v[126:129], v[130:133], v[180:183], v[126:129]
	v_mfma_f32_16x16x32_bf16 v[122:125], v[138:141], v[180:183], v[122:125]
	v_mfma_f32_16x16x32_bf16 v[110:113], v[130:133], v[188:191], v[110:113]
	v_mfma_f32_16x16x32_bf16 v[106:109], v[138:141], v[188:191], v[106:109]
	v_mfma_f32_16x16x32_bf16 v[94:97], v[130:133], v[200:203], v[94:97]
	v_mfma_f32_16x16x32_bf16 v[90:93], v[138:141], v[200:203], v[90:93]
	v_mfma_f32_16x16x32_bf16 v[82:85], v[130:133], v[208:211], v[82:85]
	v_mfma_f32_16x16x32_bf16 v[74:77], v[138:141], v[208:211], v[74:77]
	v_mfma_f32_16x16x32_bf16 v[126:129], v[134:137], v[184:187], v[126:129]
	v_mfma_f32_16x16x32_bf16 v[122:125], v[142:145], v[184:187], v[122:125]
	v_mfma_f32_16x16x32_bf16 v[110:113], v[134:137], v[196:199], v[110:113]
	v_mfma_f32_16x16x32_bf16 v[106:109], v[142:145], v[196:199], v[106:109]
	v_mfma_f32_16x16x32_bf16 v[94:97], v[134:137], v[204:207], v[94:97]
	v_mfma_f32_16x16x32_bf16 v[90:93], v[142:145], v[204:207], v[90:93]
	v_mfma_f32_16x16x32_bf16 v[82:85], v[134:137], v[212:215], v[82:85]
	v_mfma_f32_16x16x32_bf16 v[74:77], v[142:145], v[212:215], v[74:77]
	s_setprio 0
	s_setprio 1
	v_mfma_f32_16x16x32_bf16 v[118:121], v[146:149], v[180:183], v[118:121]
	v_mfma_f32_16x16x32_bf16 v[114:117], v[154:157], v[180:183], v[114:117]
	v_mfma_f32_16x16x32_bf16 v[102:105], v[146:149], v[188:191], v[102:105]
	v_mfma_f32_16x16x32_bf16 v[98:101], v[154:157], v[188:191], v[98:101]
	v_mfma_f32_16x16x32_bf16 v[86:89], v[146:149], v[200:203], v[86:89]
	v_mfma_f32_16x16x32_bf16 v[78:81], v[154:157], v[200:203], v[78:81]
	v_mfma_f32_16x16x32_bf16 v[70:73], v[146:149], v[208:211], v[70:73]
	v_mfma_f32_16x16x32_bf16 v[66:69], v[154:157], v[208:211], v[66:69]
	v_mfma_f32_16x16x32_bf16 v[118:121], v[150:153], v[184:187], v[118:121]
	v_mfma_f32_16x16x32_bf16 v[114:117], v[158:161], v[184:187], v[114:117]
	v_mfma_f32_16x16x32_bf16 v[102:105], v[150:153], v[196:199], v[102:105]
	v_mfma_f32_16x16x32_bf16 v[98:101], v[158:161], v[196:199], v[98:101]
	v_mfma_f32_16x16x32_bf16 v[86:89], v[150:153], v[204:207], v[86:89]
	v_mfma_f32_16x16x32_bf16 v[78:81], v[158:161], v[204:207], v[78:81]
	v_mfma_f32_16x16x32_bf16 v[70:73], v[150:153], v[212:215], v[70:73]
	v_mfma_f32_16x16x32_bf16 v[66:69], v[158:161], v[212:215], v[66:69]
	s_setprio 0
	s_barrier
	s_add_i32 s53, s53, s7
	s_mov_b32 m0, s53
	ds_read_b128 v[180:183], v179 offset:16384
	ds_read_b128 v[184:187], v179 offset:17408
	ds_read_b128 v[188:191], v179 offset:18432
	ds_read_b128 v[196:199], v179 offset:19456
	ds_read_b128 v[200:203], v179 offset:20480
	ds_read_b128 v[204:207], v179 offset:21504
	ds_read_b128 v[208:211], v179 offset:22528
	ds_read_b128 v[212:215], v179 offset:23552
	global_load_lds_dwordx4 v0, s[44:45]
	s_add_i32 m0, s53, 0x2000
	s_add_u32 s60, s44, 0x80000
	s_addc_u32 s61, s45, 0
	s_add_i32 s53, s66, s7
	global_load_lds_dwordx4 v162, s[44:45]
	s_mov_b32 m0, s53
	s_nop 0
	global_load_lds_dwordx4 v0, s[60:61]
	s_add_i32 m0, s53, 0x2000
	s_nop 0
	global_load_lds_dwordx4 v162, s[60:61]
	s_mov_b32 m0, s11
	s_nop 0
	global_load_lds_dwordx4 v166, s[46:47]
	s_mov_b32 m0, s16
	s_nop 0
	global_load_lds_dwordx4 v164, s[46:47]
	s_cmp_eq_u32 s51, -2
	s_cbranch_scc1 .Lfiw_2_1
	s_waitcnt vmcnt(8)
; #define PG8_STAGE(bufoff, gbase, voff) do { _Pragma("unroll") for (int _i = 0; _i < 2; ++_i) \
;         __builtin_amdgcn_global_load_lds((const unsigned*)((const char*)(gbase) + (voff)[_i]), (PG8_LAS unsigned*)(lds + (bufoff) + ldsw + _i * 8192), 16, 0, 0); } while (0)
; #define PG8_LDA(dst, b, h) do { _Pragma("unroll") for (int m = 0; m < 4; ++m) _Pragma("unroll") for (int k = 0; k < 2; ++k) dst[m][k] = *(const PG8_LAS bf16x8*)(lds + PG8_SA(b, h) + aoff + m * 2048 + k * 1024); } while (0)
; #define PG8_LDB(dst, b, h) do { _Pragma("unroll") for (int n = 0; n < 2; ++n) _Pragma("unroll") for (int k = 0; k < 2; ++k) dst[n][k] = *(const PG8_LAS bf16x8*)(lds + PG8_SB(b, h) + boff + n * 2048 + k * 1024); } while (0)
; #define PG8_MMA(ai, bj, At, Bt) do { __builtin_amdgcn_s_setprio(1); _Pragma("unroll") for (int m = 0; m < 4; ++m) _Pragma("unroll") for (int n = 0; n < 2; ++n) _Pragma("unroll") for (int k = 0; k < 2; ++k) \
;         acc[ai][bj][m][n] = __builtin_amdgcn_mfma_f32_16x16x32_bf16(Bt[n][k], At[m][k], acc[ai][bj][m][n], 0, 0, 0); __builtin_amdgcn_s_setprio(0); } while (0)
; #define PG8_WAIT_V(n) asm volatile("s_waitcnt vmcnt(" #n ")" ::: "memory")
; #define PG8_WAIT_L(n) asm volatile("s_waitcnt lgkmcnt(" #n ")" ::: "memory")
; #define PG8_BAR __builtin_amdgcn_s_barrier()
; #define PG8_SCHED __builtin_amdgcn_sched_barrier(0)
; template <class Epi, class Sched, bool ALIGN_EPI = false, bool SP2 = false>
; __device__ __forceinline__ void gemm_phase(PG8_LAS unsigned char* lds, const Sched& S, const Epi& E, int wave_id) {
;     ...
;             PG8_WAIT_V(8); PG8_WAIT_L(0); PG8_BAR; PG8_MMA(1, 0, At, B0); PG8_MMA(1, 1, At, B1); PG8_BAR; PG8_SCHED;
;             PG8_LDB(B0, 1, 0); PG8_LDB(B1, 1, 1); PG8_SCHED; PG8_LDA(At, 1, 0); PG8_STAGE(PG8_SA(0, 1), a2 + hstep, voffA);
;             PG8_WAIT_V(8); PG8_WAIT_L(0); PG8_BAR; PG8_MMA(0, 0, At, B0); PG8_MMA(0, 1, At, B1); PG8_BAR; PG8_SCHED;
.Lfiw_2_1:
	s_waitcnt lgkmcnt(0)
	s_barrier
	s_setprio 1
	s_waitcnt lgkmcnt(0)
	v_mfma_f32_16x16x32_bf16 v[62:65], v[130:133], v[180:183], v[62:65]
	v_mfma_f32_16x16x32_bf16 v[58:61], v[138:141], v[180:183], v[58:61]
	v_mfma_f32_16x16x32_bf16 v[46:49], v[130:133], v[188:191], v[46:49]
	v_mfma_f32_16x16x32_bf16 v[42:45], v[138:141], v[188:191], v[42:45]
	v_mfma_f32_16x16x32_bf16 v[34:37], v[130:133], v[200:203], v[34:37]
	v_mfma_f32_16x16x32_bf16 v[26:29], v[138:141], v[200:203], v[26:29]
	v_mfma_f32_16x16x32_bf16 v[18:21], v[130:133], v[208:211], v[18:21]
	v_mfma_f32_16x16x32_bf16 v[10:13], v[138:141], v[208:211], v[10:13]
	v_mfma_f32_16x16x32_bf16 v[62:65], v[134:137], v[184:187], v[62:65]
	v_mfma_f32_16x16x32_bf16 v[58:61], v[142:145], v[184:187], v[58:61]
	v_mfma_f32_16x16x32_bf16 v[46:49], v[134:137], v[196:199], v[46:49]
	v_mfma_f32_16x16x32_bf16 v[42:45], v[142:145], v[196:199], v[42:45]
	v_mfma_f32_16x16x32_bf16 v[34:37], v[134:137], v[204:207], v[34:37]
	v_mfma_f32_16x16x32_bf16 v[26:29], v[142:145], v[204:207], v[26:29]
	v_mfma_f32_16x16x32_bf16 v[18:21], v[134:137], v[212:215], v[18:21]
	v_mfma_f32_16x16x32_bf16 v[10:13], v[142:145], v[212:215], v[10:13]
	s_setprio 0
	s_setprio 1
	v_mfma_f32_16x16x32_bf16 v[54:57], v[146:149], v[180:183], v[54:57]
	v_mfma_f32_16x16x32_bf16 v[50:53], v[154:157], v[180:183], v[50:53]
	v_mfma_f32_16x16x32_bf16 v[38:41], v[146:149], v[188:191], v[38:41]
	v_mfma_f32_16x16x32_bf16 v[30:33], v[154:157], v[188:191], v[30:33]
	v_mfma_f32_16x16x32_bf16 v[22:25], v[146:149], v[200:203], v[22:25]
	v_mfma_f32_16x16x32_bf16 v[14:17], v[154:157], v[200:203], v[14:17]
	v_mfma_f32_16x16x32_bf16 v[6:9], v[146:149], v[208:211], v[6:9]
	v_mfma_f32_16x16x32_bf16 v[2:5], v[154:157], v[208:211], v[2:5]
	v_mfma_f32_16x16x32_bf16 v[54:57], v[150:153], v[184:187], v[54:57]
	v_mfma_f32_16x16x32_bf16 v[50:53], v[158:161], v[184:187], v[50:53]
	v_mfma_f32_16x16x32_bf16 v[38:41], v[150:153], v[196:199], v[38:41]
	v_mfma_f32_16x16x32_bf16 v[30:33], v[158:161], v[196:199], v[30:33]
	v_mfma_f32_16x16x32_bf16 v[22:25], v[150:153], v[204:207], v[22:25]
	v_mfma_f32_16x16x32_bf16 v[14:17], v[158:161], v[204:207], v[14:17]
	v_mfma_f32_16x16x32_bf16 v[6:9], v[150:153], v[212:215], v[6:9]
	v_mfma_f32_16x16x32_bf16 v[2:5], v[158:161], v[212:215], v[2:5]
	s_setprio 0
	s_barrier
	s_add_i32 s53, 0, 0x18000
	s_add_i32 s60, 0, 0x1c000
	v_add_u32_e32 v142, s53, v178
	v_add_u32_e32 v158, s60, v178
	ds_read_b128 v[130:133], v142
	ds_read_b128 v[134:137], v142 offset:1024
	ds_read_b128 v[138:141], v142 offset:2048
	ds_read_b128 v[142:145], v142 offset:3072
	ds_read_b128 v[146:149], v158
	ds_read_b128 v[150:153], v158 offset:1024
	ds_read_b128 v[154:157], v158 offset:2048
	ds_read_b128 v[158:161], v158 offset:3072
	s_add_u32 s98, s46, 0x80000
	s_addc_u32 s99, s47, 0
	s_mov_b32 m0, s17
	ds_read_b128 v[180:183], v179 offset:32768
	ds_read_b128 v[184:187], v179 offset:33792
	ds_read_b128 v[188:191], v179 offset:34816
	ds_read_b128 v[196:199], v179 offset:35840
	ds_read_b128 v[200:203], v179 offset:36864
	ds_read_b128 v[204:207], v179 offset:37888
	ds_read_b128 v[208:211], v179 offset:38912
	ds_read_b128 v[212:215], v179 offset:39936
	global_load_lds_dwordx4 v166, s[98:99]
	s_mov_b32 m0, s20
	s_nop 0
	global_load_lds_dwordx4 v164, s[98:99]
	s_waitcnt vmcnt(8)
	s_waitcnt lgkmcnt(0)
	s_barrier
	s_setprio 1
	s_waitcnt lgkmcnt(0)
	v_mfma_f32_16x16x32_bf16 v[126:129], v[130:133], v[180:183], v[126:129]
	v_mfma_f32_16x16x32_bf16 v[122:125], v[138:141], v[180:183], v[122:125]
	v_mfma_f32_16x16x32_bf16 v[110:113], v[130:133], v[188:191], v[110:113]
	v_mfma_f32_16x16x32_bf16 v[106:109], v[138:141], v[188:191], v[106:109]
	v_mfma_f32_16x16x32_bf16 v[94:97], v[130:133], v[200:203], v[94:97]
	v_mfma_f32_16x16x32_bf16 v[90:93], v[138:141], v[200:203], v[90:93]
	v_mfma_f32_16x16x32_bf16 v[82:85], v[130:133], v[208:211], v[82:85]
	v_mfma_f32_16x16x32_bf16 v[74:77], v[138:141], v[208:211], v[74:77]
	v_mfma_f32_16x16x32_bf16 v[126:129], v[134:137], v[184:187], v[126:129]
	v_mfma_f32_16x16x32_bf16 v[122:125], v[142:145], v[184:187], v[122:125]
	v_mfma_f32_16x16x32_bf16 v[110:113], v[134:137], v[196:199], v[110:113]
	v_mfma_f32_16x16x32_bf16 v[106:109], v[142:145], v[196:199], v[106:109]
	v_mfma_f32_16x16x32_bf16 v[94:97], v[134:137], v[204:207], v[94:97]
	v_mfma_f32_16x16x32_bf16 v[90:93], v[142:145], v[204:207], v[90:93]
	v_mfma_f32_16x16x32_bf16 v[82:85], v[134:137], v[212:215], v[82:85]
	v_mfma_f32_16x16x32_bf16 v[74:77], v[142:145], v[212:215], v[74:77]
	s_setprio 0
	s_setprio 1
	v_mfma_f32_16x16x32_bf16 v[118:121], v[146:149], v[180:183], v[118:121]
	v_mfma_f32_16x16x32_bf16 v[114:117], v[154:157], v[180:183], v[114:117]
	v_mfma_f32_16x16x32_bf16 v[102:105], v[146:149], v[188:191], v[102:105]
	v_mfma_f32_16x16x32_bf16 v[98:101], v[154:157], v[188:191], v[98:101]
	v_mfma_f32_16x16x32_bf16 v[86:89], v[146:149], v[200:203], v[86:89]
	v_mfma_f32_16x16x32_bf16 v[78:81], v[154:157], v[200:203], v[78:81]
	v_mfma_f32_16x16x32_bf16 v[70:73], v[146:149], v[208:211], v[70:73]
	v_mfma_f32_16x16x32_bf16 v[66:69], v[154:157], v[208:211], v[66:69]
	v_mfma_f32_16x16x32_bf16 v[118:121], v[150:153], v[184:187], v[118:121]
	v_mfma_f32_16x16x32_bf16 v[114:117], v[158:161], v[184:187], v[114:117]
	v_mfma_f32_16x16x32_bf16 v[102:105], v[150:153], v[196:199], v[102:105]
	v_mfma_f32_16x16x32_bf16 v[98:101], v[158:161], v[196:199], v[98:101]
	v_mfma_f32_16x16x32_bf16 v[86:89], v[150:153], v[204:207], v[86:89]
	v_mfma_f32_16x16x32_bf16 v[78:81], v[158:161], v[204:207], v[78:81]
	v_mfma_f32_16x16x32_bf16 v[70:73], v[150:153], v[212:215], v[70:73]
	v_mfma_f32_16x16x32_bf16 v[66:69], v[158:161], v[212:215], v[66:69]
	s_setprio 0
	s_barrier
; #define PG8_STAGE(bufoff, gbase, voff) do { _Pragma("unroll") for (int _i = 0; _i < 2; ++_i) \
;         __builtin_amdgcn_global_load_lds((const unsigned*)((const char*)(gbase) + (voff)[_i]), (PG8_LAS unsigned*)(lds + (bufoff) + ldsw + _i * 8192), 16, 0, 0); } while (0)
; #define PG8_LDA(dst, b, h) do { _Pragma("unroll") for (int m = 0; m < 4; ++m) _Pragma("unroll") for (int k = 0; k < 2; ++k) dst[m][k] = *(const PG8_LAS bf16x8*)(lds + PG8_SA(b, h) + aoff + m * 2048 + k * 1024); } while (0)
; #define PG8_MMA(ai, bj, At, Bt) do { __builtin_amdgcn_s_setprio(1); _Pragma("unroll") for (int m = 0; m < 4; ++m) _Pragma("unroll") for (int n = 0; n < 2; ++n) _Pragma("unroll") for (int k = 0; k < 2; ++k) \
;         acc[ai][bj][m][n] = __builtin_amdgcn_mfma_f32_16x16x32_bf16(Bt[n][k], At[m][k], acc[ai][bj][m][n], 0, 0, 0); __builtin_amdgcn_s_setprio(0); } while (0)
; #define PG8_WAIT_V(n) asm volatile("s_waitcnt vmcnt(" #n ")" ::: "memory")
; #define PG8_WAIT_L(n) asm volatile("s_waitcnt lgkmcnt(" #n ")" ::: "memory")
; #define PG8_BAR __builtin_amdgcn_s_barrier()
; #define PG8_SCHED __builtin_amdgcn_sched_barrier(0)
; template <class Epi, class Sched, bool ALIGN_EPI = false, bool SP2 = false>
; __device__ __forceinline__ void gemm_phase(PG8_LAS unsigned char* lds, const Sched& S, const Epi& E, int wave_id) {
;     ...
;             PG8_LDA(At, 1, 1); PG8_STAGE(PG8_SB(1, 0), b3, voffB); PG8_STAGE(PG8_SB(1, 1), b3 + hstep, voffB); PG8_STAGE(PG8_SA(1, 0), a3, voffA);
;             PG8_WAIT_V(8); PG8_WAIT_L(0); PG8_BAR; PG8_MMA(1, 0, At, B0); PG8_MMA(1, 1, At, B1); PG8_BAR; PG8_SCHED;
	s_add_i32 s100, s53, s7
	s_sub_i32 m0, s100, 0x80
	ds_read_b128 v[180:183], v179 offset:49152
	ds_read_b128 v[184:187], v179 offset:50176
	ds_read_b128 v[188:191], v179 offset:51200
	ds_read_b128 v[196:199], v179 offset:52224
	ds_read_b128 v[200:203], v179 offset:53248
	ds_read_b128 v[204:207], v179 offset:54272
	ds_read_b128 v[208:211], v179 offset:55296
	ds_read_b128 v[212:215], v179 offset:56320
	global_load_lds_dwordx4 v0, s[44:45] offset:128
	s_add_i32 m0, s100, 0x1f80
	s_add_i32 s100, s60, s7
	global_load_lds_dwordx4 v162, s[44:45] offset:128
	s_add_u32 s44, s44, 0x80080
	s_addc_u32 s45, s45, 0
	s_mov_b32 m0, s100
	s_nop 0
	global_load_lds_dwordx4 v0, s[44:45]
	s_add_i32 m0, s100, 0x2000
	s_nop 0
	global_load_lds_dwordx4 v162, s[44:45]
	s_sub_i32 m0, s23, 0x80
	s_nop 0
	global_load_lds_dwordx4 v166, s[46:47] offset:128
	s_sub_i32 m0, s24, 0x80
	s_nop 0
	global_load_lds_dwordx4 v164, s[46:47] offset:128
	s_waitcnt vmcnt(8)
	s_waitcnt lgkmcnt(0)
	s_barrier
	s_setprio 1
	s_waitcnt lgkmcnt(0)
	v_mfma_f32_16x16x32_bf16 v[62:65], v[130:133], v[180:183], v[62:65]
	v_mfma_f32_16x16x32_bf16 v[58:61], v[138:141], v[180:183], v[58:61]
	v_mfma_f32_16x16x32_bf16 v[46:49], v[130:133], v[188:191], v[46:49]
	v_mfma_f32_16x16x32_bf16 v[42:45], v[138:141], v[188:191], v[42:45]
	v_mfma_f32_16x16x32_bf16 v[34:37], v[130:133], v[200:203], v[34:37]
	v_mfma_f32_16x16x32_bf16 v[26:29], v[138:141], v[200:203], v[26:29]
	v_mfma_f32_16x16x32_bf16 v[18:21], v[130:133], v[208:211], v[18:21]
	v_mfma_f32_16x16x32_bf16 v[10:13], v[138:141], v[208:211], v[10:13]
	v_mfma_f32_16x16x32_bf16 v[62:65], v[134:137], v[184:187], v[62:65]
	v_mfma_f32_16x16x32_bf16 v[58:61], v[142:145], v[184:187], v[58:61]
	v_mfma_f32_16x16x32_bf16 v[46:49], v[134:137], v[196:199], v[46:49]
	v_mfma_f32_16x16x32_bf16 v[42:45], v[142:145], v[196:199], v[42:45]
	v_mfma_f32_16x16x32_bf16 v[34:37], v[134:137], v[204:207], v[34:37]
	v_mfma_f32_16x16x32_bf16 v[26:29], v[142:145], v[204:207], v[26:29]
	v_mfma_f32_16x16x32_bf16 v[18:21], v[134:137], v[212:215], v[18:21]
	v_mfma_f32_16x16x32_bf16 v[10:13], v[142:145], v[212:215], v[10:13]
	s_setprio 0
	s_setprio 1
	v_mfma_f32_16x16x32_bf16 v[54:57], v[146:149], v[180:183], v[54:57]
	v_mfma_f32_16x16x32_bf16 v[50:53], v[154:157], v[180:183], v[50:53]
	v_mfma_f32_16x16x32_bf16 v[38:41], v[146:149], v[188:191], v[38:41]
	v_mfma_f32_16x16x32_bf16 v[30:33], v[154:157], v[188:191], v[30:33]
	v_mfma_f32_16x16x32_bf16 v[22:25], v[146:149], v[200:203], v[22:25]
	v_mfma_f32_16x16x32_bf16 v[14:17], v[154:157], v[200:203], v[14:17]
	v_mfma_f32_16x16x32_bf16 v[6:9], v[146:149], v[208:211], v[6:9]
	v_mfma_f32_16x16x32_bf16 v[2:5], v[154:157], v[208:211], v[2:5]
	v_mfma_f32_16x16x32_bf16 v[54:57], v[150:153], v[184:187], v[54:57]
	v_mfma_f32_16x16x32_bf16 v[50:53], v[158:161], v[184:187], v[50:53]
	v_mfma_f32_16x16x32_bf16 v[38:41], v[150:153], v[196:199], v[38:41]
	v_mfma_f32_16x16x32_bf16 v[30:33], v[158:161], v[196:199], v[30:33]
	v_mfma_f32_16x16x32_bf16 v[22:25], v[150:153], v[204:207], v[22:25]
	v_mfma_f32_16x16x32_bf16 v[14:17], v[158:161], v[204:207], v[14:17]
	v_mfma_f32_16x16x32_bf16 v[6:9], v[150:153], v[212:215], v[6:9]
	v_mfma_f32_16x16x32_bf16 v[2:5], v[158:161], v[212:215], v[2:5]
	s_setprio 0
	s_barrier
	s_add_i32 s51, s51, 2
	s_add_u32 s42, s42, 0x100
	s_addc_u32 s43, s43, 0
	s_add_u32 s19, s19, 0x100
	s_addc_u32 s50, s50, 0
	s_cmp_gt_u32 s51, 29
	s_cbranch_scc0 .LBB0_1039
	s_and_b64 vcc, exec, s[12:13]
	s_cbranch_vccz .LBB0_1042
	s_barrier
